# P9 GEMM epilogue hand-rewritten: 32 residual loads issued up front, counted vmcnt (on top of skinny rewrite + LDS read hoisting in ssd_prompt)
# speedup vs baseline: 1.0332x; 1.0065x over previous
.LBB0_480:
	ds_read_b32 v75, v129
	s_mov_b64 s[84:85], -1
	s_mov_b64 s[14:15], 0
	s_cmp_lt_i32 s64, 3
	s_mov_b64 s[30:31], 0
	s_cbranch_scc1 .LBB0_495
	s_cmp_gt_i32 s64, 4
	s_cbranch_scc0 .LBB0_486
	s_cmp_gt_i32 s64, 5
	s_cbranch_scc0 .LBB0_487
	s_cmp_eq_u32 s64, 6
	s_mov_b64 s[30:31], -1
	s_cbranch_scc0 .LBB0_485
	ds_read_b128 v[194:197], v79 offset:34816
	ds_read_b128 v[198:201], v79 offset:39168
	ds_read_b128 v[202:205], v78
	ds_read_b128 v[206:209], v79 offset:60928
	ds_read_b128 v[210:213], v79 offset:43520
	ds_read_b128 v[214:217], v79 offset:47872
	ds_read_b128 v[218:221], v79 offset:52224
	ds_read_b128 v[222:225], v79 offset:56576
	ds_read_b128 v[226:229], v78 offset:64
	ds_read_b128 v[230:233], v79 offset:34880
	s_waitcnt lgkmcnt(7)
	v_mfma_f32_16x16x32_bf16 v[48:51], v[194:197], v[202:205], 0
	ds_read_b128 v[194:197], v79 offset:39232
	v_mfma_f32_16x16x32_bf16 v[52:55], v[198:201], v[202:205], 0
	ds_read_b128 v[198:201], v79 offset:43584
	s_waitcnt lgkmcnt(7)
	v_mfma_f32_16x16x32_bf16 v[64:67], v[210:213], v[202:205], 0
	ds_read_b128 v[210:213], v79 offset:47936
	s_waitcnt lgkmcnt(7)
	v_mfma_f32_16x16x32_bf16 v[100:103], v[214:217], v[202:205], 0
	ds_read_b128 v[214:217], v79 offset:52288
	s_waitcnt lgkmcnt(7)
	v_mfma_f32_16x16x32_bf16 v[104:107], v[218:221], v[202:205], 0
	ds_read_b128 v[218:221], v79 offset:56640
	s_waitcnt lgkmcnt(7)
	v_mfma_f32_16x16x32_bf16 v[166:169], v[222:225], v[202:205], 0
	ds_read_b128 v[222:225], v79 offset:60992
	v_mfma_f32_16x16x32_bf16 v[56:59], v[206:209], v[202:205], 0
	ds_read_b128 v[202:205], v78 offset:128
	ds_read_b128 v[206:209], v79 offset:34944
	s_waitcnt lgkmcnt(8)
	v_mfma_f32_16x16x32_bf16 v[48:51], v[230:233], v[226:229], v[48:51]
	ds_read_b128 v[230:233], v79 offset:39296
	s_waitcnt lgkmcnt(8)
	v_mfma_f32_16x16x32_bf16 v[52:55], v[194:197], v[226:229], v[52:55]
	ds_read_b128 v[194:197], v79 offset:43648
	s_waitcnt lgkmcnt(8)
	v_mfma_f32_16x16x32_bf16 v[64:67], v[198:201], v[226:229], v[64:67]
	ds_read_b128 v[198:201], v79 offset:48000
	s_waitcnt lgkmcnt(8)
	v_mfma_f32_16x16x32_bf16 v[100:103], v[210:213], v[226:229], v[100:103]
	ds_read_b128 v[210:213], v79 offset:52352
	s_waitcnt lgkmcnt(8)
	v_mfma_f32_16x16x32_bf16 v[104:107], v[214:217], v[226:229], v[104:107]
	ds_read_b128 v[214:217], v79 offset:56704
	s_waitcnt lgkmcnt(8)
	v_mfma_f32_16x16x32_bf16 v[166:169], v[218:221], v[226:229], v[166:169]
	ds_read_b128 v[218:221], v79 offset:61056
	ds_read_b128 v[178:181], v78 offset:192
	s_waitcnt lgkmcnt(9)
	v_mfma_f32_16x16x32_bf16 v[56:59], v[222:225], v[226:229], v[56:59]
	ds_read_b128 v[222:225], v79 offset:35008
	ds_read_b128 v[226:229], v79 offset:39360
	s_waitcnt lgkmcnt(9)
	v_mfma_f32_16x16x32_bf16 v[48:51], v[206:209], v[202:205], v[48:51]
	ds_read_b128 v[206:209], v79 offset:43712
	s_waitcnt lgkmcnt(9)
	v_mfma_f32_16x16x32_bf16 v[52:55], v[230:233], v[202:205], v[52:55]
	ds_read_b128 v[230:233], v79 offset:48064
	s_waitcnt lgkmcnt(9)
	v_mfma_f32_16x16x32_bf16 v[64:67], v[194:197], v[202:205], v[64:67]
	ds_read_b128 v[194:197], v79 offset:52416
	s_waitcnt lgkmcnt(9)
	v_mfma_f32_16x16x32_bf16 v[100:103], v[198:201], v[202:205], v[100:103]
	ds_read_b128 v[198:201], v79 offset:56768
	s_waitcnt lgkmcnt(9)
	v_mfma_f32_16x16x32_bf16 v[104:107], v[210:213], v[202:205], v[104:107]
	ds_read_b128 v[210:213], v79 offset:61120
	s_waitcnt lgkmcnt(9)
	v_mfma_f32_16x16x32_bf16 v[166:169], v[214:217], v[202:205], v[166:169]
	ds_read_b128 v[214:217], v131
	s_waitcnt lgkmcnt(9)
	v_mfma_f32_16x16x32_bf16 v[174:177], v[218:221], v[202:205], v[56:59]
	ds_read_b128 v[202:205], v132
	ds_read_b128 v[218:221], v133
	s_nop 1
	v_mov_b32_e32 v3, v130
	s_waitcnt lgkmcnt(9)
	v_mfma_f32_16x16x32_bf16 v[182:185], v[222:225], v[178:181], v[48:51]
	ds_read_b128 v[222:225], v134
	s_nop 2
	s_waitcnt lgkmcnt(9)
	v_mfma_f32_16x16x32_bf16 v[186:189], v[226:229], v[178:181], v[52:55]
	ds_read_b128 v[226:229], v135
	s_waitcnt lgkmcnt(9)
	v_mfma_f32_16x16x32_bf16 v[190:193], v[206:209], v[178:181], v[64:67]
	ds_read_b128 v[206:209], v136
	s_waitcnt lgkmcnt(9)
	v_mfma_f32_16x16x32_bf16 v[60:63], v[230:233], v[178:181], v[100:103]
	ds_read_b128 v[230:233], v137
	s_waitcnt lgkmcnt(9)
	v_mfma_f32_16x16x32_bf16 v[56:59], v[194:197], v[178:181], v[104:107]
	ds_read_b128 v[194:197], v138
	s_waitcnt lgkmcnt(9)
	v_mfma_f32_16x16x32_bf16 v[52:55], v[198:201], v[178:181], v[166:169]
	ds_read_b128 v[198:201], v139
	s_waitcnt lgkmcnt(9)
	v_mfma_f32_16x16x32_bf16 v[48:51], v[210:213], v[178:181], v[174:177]
	ds_read_b128 v[210:213], v140
	s_waitcnt lgkmcnt(9)
	v_sub_f32_e32 v0, v75, v214
	v_sub_f32_e32 v1, v75, v215
	v_sub_f32_e32 v64, v75, v216
	v_sub_f32_e32 v65, v75, v217
	ds_read_b128 v[214:217], v141
	v_mul_f32_e32 v0, 0x3fb8aa3b, v0
	v_mul_f32_e32 v1, 0x3fb8aa3b, v1
	v_mul_f32_e32 v64, 0x3fb8aa3b, v64
	v_mul_f32_e32 v65, 0x3fb8aa3b, v65
	v_exp_f32_e32 v0, v0
	v_exp_f32_e32 v1, v1
	v_exp_f32_e32 v64, v64
	v_exp_f32_e32 v65, v65
	v_pk_mul_f32 v[0:1], v[182:183], v[0:1]
	s_waitcnt lgkmcnt(9)
	v_pk_mul_f32 v[0:1], v[202:203], v[0:1]
	v_pk_mul_f32 v[64:65], v[184:185], v[64:65]
	s_nop 0
	v_pk_mul_f32 v[64:65], v[204:205], v[64:65]
	ds_read_b128 v[202:205], v142
	s_waitcnt lgkmcnt(9)
	v_sub_f32_e32 v66, v75, v218
	v_sub_f32_e32 v67, v75, v219
	v_sub_f32_e32 v100, v75, v220
	v_sub_f32_e32 v101, v75, v221
	ds_read_b128 v[218:221], v143
	v_mul_f32_e32 v66, 0x3fb8aa3b, v66
	v_mul_f32_e32 v67, 0x3fb8aa3b, v67
	v_mul_f32_e32 v100, 0x3fb8aa3b, v100
	v_mul_f32_e32 v101, 0x3fb8aa3b, v101
	v_exp_f32_e32 v66, v66
	v_exp_f32_e32 v67, v67
	v_exp_f32_e32 v100, v100
	v_exp_f32_e32 v101, v101
	v_pk_mul_f32 v[66:67], v[186:187], v[66:67]
	s_waitcnt lgkmcnt(9)
	v_pk_mul_f32 v[66:67], v[222:223], v[66:67]
	v_pk_mul_f32 v[100:101], v[188:189], v[100:101]
	s_nop 0
	v_pk_mul_f32 v[100:101], v[224:225], v[100:101]
	ds_read_b128 v[222:225], v144
	s_waitcnt lgkmcnt(9)
	v_sub_f32_e32 v102, v75, v226
	v_sub_f32_e32 v103, v75, v227
	v_sub_f32_e32 v104, v75, v228
	v_sub_f32_e32 v105, v75, v229
	v_mul_f32_e32 v102, 0x3fb8aa3b, v102
	v_mul_f32_e32 v103, 0x3fb8aa3b, v103
	v_mul_f32_e32 v104, 0x3fb8aa3b, v104
	v_mul_f32_e32 v105, 0x3fb8aa3b, v105
	v_exp_f32_e32 v102, v102
	v_exp_f32_e32 v103, v103
	v_exp_f32_e32 v104, v104
	v_exp_f32_e32 v105, v105
	v_pk_mul_f32 v[102:103], v[190:191], v[102:103]
	s_waitcnt lgkmcnt(8)
	v_pk_mul_f32 v[102:103], v[206:207], v[102:103]
	v_pk_mul_f32 v[104:105], v[192:193], v[104:105]
	s_nop 0
	v_pk_mul_f32 v[104:105], v[208:209], v[104:105]
	s_waitcnt lgkmcnt(7)
	v_sub_f32_e32 v106, v75, v230
	v_sub_f32_e32 v107, v75, v231
	v_mul_f32_e32 v106, 0x3fb8aa3b, v106
	v_mul_f32_e32 v107, 0x3fb8aa3b, v107
	v_exp_f32_e32 v106, v106
	v_exp_f32_e32 v107, v107
	s_nop 0
	v_pk_mul_f32 v[60:61], v[60:61], v[106:107]
	v_sub_f32_e32 v106, v75, v232
	v_sub_f32_e32 v107, v75, v233
	v_mul_f32_e32 v106, 0x3fb8aa3b, v106
	v_mul_f32_e32 v107, 0x3fb8aa3b, v107
	v_exp_f32_e32 v106, v106
	v_exp_f32_e32 v107, v107
	s_waitcnt lgkmcnt(6)
	v_pk_mul_f32 v[60:61], v[194:195], v[60:61]
	v_pk_mul_f32 v[62:63], v[62:63], v[106:107]
	s_nop 0
	v_pk_mul_f32 v[62:63], v[196:197], v[62:63]
	s_waitcnt lgkmcnt(5)
	v_sub_f32_e32 v106, v75, v198
	v_sub_f32_e32 v107, v75, v199
	v_mul_f32_e32 v106, 0x3fb8aa3b, v106
	v_mul_f32_e32 v107, 0x3fb8aa3b, v107
	v_exp_f32_e32 v106, v106
	v_exp_f32_e32 v107, v107
	s_nop 0
	v_pk_mul_f32 v[56:57], v[56:57], v[106:107]
	v_sub_f32_e32 v106, v75, v200
	v_sub_f32_e32 v107, v75, v201
	v_mul_f32_e32 v106, 0x3fb8aa3b, v106
	v_mul_f32_e32 v107, 0x3fb8aa3b, v107
	v_exp_f32_e32 v106, v106
	v_exp_f32_e32 v107, v107
	s_waitcnt lgkmcnt(4)
	v_pk_mul_f32 v[56:57], v[210:211], v[56:57]
	v_pk_mul_f32 v[58:59], v[58:59], v[106:107]
	s_nop 0
	v_pk_mul_f32 v[58:59], v[212:213], v[58:59]
	s_waitcnt lgkmcnt(3)
	v_sub_f32_e32 v106, v75, v214
	v_sub_f32_e32 v107, v75, v215
	v_mul_f32_e32 v106, 0x3fb8aa3b, v106
	v_mul_f32_e32 v107, 0x3fb8aa3b, v107
	v_exp_f32_e32 v106, v106
	v_exp_f32_e32 v107, v107
	s_nop 0
	v_pk_mul_f32 v[52:53], v[52:53], v[106:107]
	v_sub_f32_e32 v106, v75, v216
	v_sub_f32_e32 v107, v75, v217
	v_mul_f32_e32 v106, 0x3fb8aa3b, v106
	v_mul_f32_e32 v107, 0x3fb8aa3b, v107
	v_exp_f32_e32 v106, v106
	v_exp_f32_e32 v107, v107
	s_waitcnt lgkmcnt(2)
	v_pk_mul_f32 v[52:53], v[202:203], v[52:53]
	v_pk_mul_f32 v[54:55], v[54:55], v[106:107]
	s_nop 0
	v_pk_mul_f32 v[54:55], v[204:205], v[54:55]
	s_waitcnt lgkmcnt(1)
	v_sub_f32_e32 v106, v75, v218
	v_sub_f32_e32 v107, v75, v219
	v_mul_f32_e32 v106, 0x3fb8aa3b, v106
	v_mul_f32_e32 v107, 0x3fb8aa3b, v107
	v_exp_f32_e32 v106, v106
	v_exp_f32_e32 v107, v107
	s_nop 0
	v_pk_mul_f32 v[48:49], v[48:49], v[106:107]
	v_sub_f32_e32 v106, v75, v220
	v_sub_f32_e32 v107, v75, v221
	v_mul_f32_e32 v106, 0x3fb8aa3b, v106
	v_mul_f32_e32 v107, 0x3fb8aa3b, v107
	v_exp_f32_e32 v106, v106
	v_exp_f32_e32 v107, v107
	s_waitcnt lgkmcnt(0)
	v_pk_mul_f32 v[48:49], v[222:223], v[48:49]
	v_pk_mul_f32 v[50:51], v[50:51], v[106:107]
	s_nop 0
	v_pk_mul_f32 v[50:51], v[224:225], v[50:51]
	v_cvt_pk_bf16_f32 v0, v0, v1
	v_cmp_lt_i32_e32 vcc, -1, v3
	v_add_u32_e32 v170, v145, v146
	s_nop 0
	v_cndmask_b32_e32 v1, 0, v0, vcc
	v_lshrrev_b32_e32 v0, 16, v0
	v_cmp_lt_i32_e32 vcc, 0, v3
	s_nop 1
	v_cndmask_b32_e32 v0, 0, v0, vcc
	v_perm_b32 v106, v0, v1, s69
	v_cvt_pk_bf16_f32 v0, v64, v65
	v_cmp_lt_i32_e32 vcc, 1, v3
	s_nop 1
	v_cndmask_b32_e32 v1, 0, v0, vcc
	v_lshrrev_b32_e32 v0, 16, v0
	v_cmp_lt_i32_e32 vcc, 2, v3
	s_nop 1
	v_cndmask_b32_e32 v0, 0, v0, vcc
	v_perm_b32 v107, v0, v1, s69
	v_cvt_pk_bf16_f32 v0, v66, v67
	v_cmp_lt_i32_e32 vcc, 15, v3
	ds_read_b64_tr_b16 v[66:67], v170 offset:1280
	ds_read_b64_tr_b16 v[64:65], v170
	v_cndmask_b32_e32 v1, 0, v0, vcc
	v_lshrrev_b32_e32 v0, 16, v0
	v_cmp_lt_i32_e32 vcc, 16, v3
	ds_read_b64_tr_b16 v[168:169], v170 offset:1312
	ds_read_b64_tr_b16 v[166:167], v170 offset:32
	v_cndmask_b32_e32 v0, 0, v0, vcc
	v_perm_b32 v108, v0, v1, s69
	v_cvt_pk_bf16_f32 v0, v100, v101
	v_cmp_lt_i32_e32 vcc, 17, v3
	s_nop 1
	v_cndmask_b32_e32 v1, 0, v0, vcc
	v_lshrrev_b32_e32 v0, 16, v0
	v_cmp_lt_i32_e32 vcc, 18, v3
	s_nop 1
	v_cndmask_b32_e32 v0, 0, v0, vcc
	v_perm_b32 v109, v0, v1, s69
	s_nop 0
	s_waitcnt lgkmcnt(2)
	v_mfma_f32_16x16x32_bf16 v[64:67], v[64:67], v[106:109], 0
	s_waitcnt lgkmcnt(0)
	v_mfma_f32_16x16x32_bf16 v[106:109], v[166:169], v[106:109], 0
	v_cvt_pk_bf16_f32 v0, v102, v103
	v_cmp_lt_i32_e32 vcc, 31, v3
	s_nop 1
	v_cndmask_b32_e32 v1, 0, v0, vcc
	v_lshrrev_b32_e32 v0, 16, v0
	v_cmp_lt_i32_e32 vcc, 32, v3
	s_nop 1
	v_cndmask_b32_e32 v0, 0, v0, vcc
	v_perm_b32 v100, v0, v1, s69
	v_cvt_pk_bf16_f32 v0, v104, v105
	v_cmp_lt_i32_e32 vcc, 33, v3
	s_nop 1
	v_cndmask_b32_e32 v1, 0, v0, vcc
	v_lshrrev_b32_e32 v0, 16, v0
	v_cmp_lt_i32_e32 vcc, 34, v3
	s_nop 1
	v_cndmask_b32_e32 v0, 0, v0, vcc
	v_perm_b32 v101, v0, v1, s69
	v_cvt_pk_bf16_f32 v0, v60, v61
	v_cmp_lt_i32_e32 vcc, 47, v3
	s_nop 1
	v_cndmask_b32_e32 v1, 0, v0, vcc
	v_lshrrev_b32_e32 v0, 16, v0
	v_cmp_lt_i32_e32 vcc, 48, v3
	s_nop 1
	v_cndmask_b32_e32 v0, 0, v0, vcc
	v_perm_b32 v102, v0, v1, s69
	v_cvt_pk_bf16_f32 v0, v62, v63
	ds_read_b64_tr_b16 v[62:63], v170 offset:3840
	ds_read_b64_tr_b16 v[60:61], v170 offset:2560
	ds_read_b64_tr_b16 v[166:167], v170 offset:2592
	ds_read_b64_tr_b16 v[168:169], v170 offset:3872
	v_cmp_lt_i32_e32 vcc, 49, v3
	s_nop 1
	v_cndmask_b32_e32 v1, 0, v0, vcc
	v_lshrrev_b32_e32 v0, 16, v0
	v_cmp_lt_i32_e32 vcc, 50, v3
	s_nop 1
	v_cndmask_b32_e32 v0, 0, v0, vcc
	v_perm_b32 v103, v0, v1, s69
	s_nop 0
	s_waitcnt lgkmcnt(2)
	v_mfma_f32_16x16x32_bf16 v[60:63], v[60:63], v[100:103], v[64:67]
	s_waitcnt lgkmcnt(0)
	v_mfma_f32_16x16x32_bf16 v[64:67], v[166:169], v[100:103], v[106:109]
	v_cvt_pk_bf16_f32 v0, v56, v57
	v_cmp_lt_i32_e32 vcc, 63, v3
	s_nop 1
	v_cndmask_b32_e32 v1, 0, v0, vcc
	v_lshrrev_b32_e32 v0, 16, v0
	v_cmp_lt_i32_e32 vcc, 64, v3
	s_nop 1
	v_cndmask_b32_e32 v0, 0, v0, vcc
	v_perm_b32 v56, v0, v1, s69
	v_cvt_pk_bf16_f32 v0, v58, v59
	v_cmp_lt_i32_e32 vcc, s86, v3
	s_nop 1
	v_cndmask_b32_e32 v1, 0, v0, vcc
	v_lshrrev_b32_e32 v0, 16, v0
	v_cmp_lt_i32_e32 vcc, s88, v3
	s_nop 1
	v_cndmask_b32_e32 v0, 0, v0, vcc
	v_perm_b32 v57, v0, v1, s69
	v_cvt_pk_bf16_f32 v0, v52, v53
	v_cmp_lt_i32_e32 vcc, s52, v3
	s_nop 1
	v_cndmask_b32_e32 v1, 0, v0, vcc
	v_lshrrev_b32_e32 v0, 16, v0
	v_cmp_lt_i32_e32 vcc, s97, v3
	s_nop 1
	v_cndmask_b32_e32 v0, 0, v0, vcc
	v_perm_b32 v58, v0, v1, s69
	v_cvt_pk_bf16_f32 v0, v54, v55
	ds_read_b64_tr_b16 v[54:55], v170 offset:6400
	ds_read_b64_tr_b16 v[52:53], v170 offset:5120
	ds_read_b64_tr_b16 v[100:101], v170 offset:5152
	ds_read_b64_tr_b16 v[102:103], v170 offset:6432
	v_cmp_lt_i32_e32 vcc, s53, v3
	s_nop 1
	v_cndmask_b32_e32 v1, 0, v0, vcc
	v_lshrrev_b32_e32 v0, 16, v0
	v_cmp_lt_i32_e32 vcc, s54, v3
	s_nop 1
	v_cndmask_b32_e32 v0, 0, v0, vcc
	v_perm_b32 v59, v0, v1, s69
	s_nop 0
	s_waitcnt lgkmcnt(2)
	v_mfma_f32_16x16x32_bf16 v[52:55], v[52:55], v[56:59], v[60:63]
	s_waitcnt lgkmcnt(0)
	v_mfma_f32_16x16x32_bf16 v[56:59], v[100:103], v[56:59], v[64:67]
	v_cvt_pk_bf16_f32 v0, v48, v49
	v_cmp_lt_i32_e32 vcc, s55, v3
	s_mov_b64 s[30:31], 0
	s_nop 0
	v_cndmask_b32_e32 v1, 0, v0, vcc
	v_lshrrev_b32_e32 v0, 16, v0
	v_cmp_lt_i32_e32 vcc, s68, v3
	s_nop 1
	v_cndmask_b32_e32 v0, 0, v0, vcc
	v_perm_b32 v0, v0, v1, s69
	v_cvt_pk_bf16_f32 v1, v50, v51
	v_cmp_lt_i32_e32 vcc, s56, v3
	s_nop 1
	v_cndmask_b32_e32 v48, 0, v1, vcc
	v_lshrrev_b32_e32 v1, 16, v1
	v_cmp_lt_i32_e32 vcc, s57, v3
	v_mov_b32_e32 v3, v2
	s_nop 0
	v_cndmask_b32_e32 v1, 0, v1, vcc
	v_perm_b32 v1, v1, v48, s69
	ds_read_b64_tr_b16 v[50:51], v170 offset:8960
	ds_read_b64_tr_b16 v[48:49], v170 offset:7680
	ds_read_b64_tr_b16 v[60:61], v170 offset:7712
	ds_read_b64_tr_b16 v[62:63], v170 offset:8992
	s_waitcnt lgkmcnt(2)
	v_mfma_f32_16x16x32_bf16 v[48:51], v[48:51], v[0:3], v[52:55]
	s_waitcnt lgkmcnt(0)
	v_mfma_f32_16x16x32_bf16 v[52:55], v[60:63], v[0:3], v[56:59]

.LBB0_487:
	s_and_b64 vcc, exec, s[84:85]
	s_cbranch_vccz .LBB0_489
	ds_read_b128 v[194:197], v79 offset:34816
	ds_read_b128 v[198:201], v78
	ds_read_b128 v[202:205], v79 offset:39168
	ds_read_b128 v[206:209], v79 offset:43520
	ds_read_b128 v[210:213], v79 offset:47872
	ds_read_b128 v[214:217], v79 offset:52224
	ds_read_b128 v[218:221], v79 offset:56576
	ds_read_b128 v[222:225], v78 offset:64
	ds_read_b128 v[226:229], v79 offset:34880
	ds_read_b128 v[230:233], v79 offset:39232
	s_waitcnt lgkmcnt(8)
	v_mfma_f32_16x16x32_bf16 v[48:51], v[194:197], v[198:201], 0
	ds_read_b128 v[194:197], v79 offset:43584
	s_waitcnt lgkmcnt(8)
	v_mfma_f32_16x16x32_bf16 v[56:59], v[202:205], v[198:201], 0
	ds_read_b128 v[202:205], v79 offset:47936
	s_waitcnt lgkmcnt(8)
	v_mfma_f32_16x16x32_bf16 v[60:63], v[206:209], v[198:201], 0
	ds_read_b128 v[206:209], v79 offset:52288
	s_waitcnt lgkmcnt(8)
	v_mfma_f32_16x16x32_bf16 v[64:67], v[210:213], v[198:201], 0
	ds_read_b128 v[210:213], v79 offset:56640
	s_waitcnt lgkmcnt(8)
	v_mfma_f32_16x16x32_bf16 v[100:103], v[214:217], v[198:201], 0
	ds_read_b128 v[214:217], v78 offset:128
	s_waitcnt lgkmcnt(8)
	v_mfma_f32_16x16x32_bf16 v[52:55], v[218:221], v[198:201], 0
	ds_read_b128 v[198:201], v79 offset:34944
	ds_read_b128 v[218:221], v79 offset:39296
	s_waitcnt lgkmcnt(8)
	v_mfma_f32_16x16x32_bf16 v[48:51], v[226:229], v[222:225], v[48:51]
	ds_read_b128 v[226:229], v79 offset:43648
	s_waitcnt lgkmcnt(8)
	v_mfma_f32_16x16x32_bf16 v[56:59], v[230:233], v[222:225], v[56:59]
	ds_read_b128 v[230:233], v79 offset:48000
	s_waitcnt lgkmcnt(8)
	v_mfma_f32_16x16x32_bf16 v[60:63], v[194:197], v[222:225], v[60:63]
	ds_read_b128 v[194:197], v79 offset:52352
	s_waitcnt lgkmcnt(8)
	v_mfma_f32_16x16x32_bf16 v[64:67], v[202:205], v[222:225], v[64:67]
	ds_read_b128 v[202:205], v79 offset:56704
	s_waitcnt lgkmcnt(8)
	v_mfma_f32_16x16x32_bf16 v[100:103], v[206:209], v[222:225], v[100:103]
	s_waitcnt lgkmcnt(7)
	v_mfma_f32_16x16x32_bf16 v[52:55], v[210:213], v[222:225], v[52:55]
	s_waitcnt lgkmcnt(5)
	v_mfma_f32_16x16x32_bf16 v[48:51], v[198:201], v[214:217], v[48:51]
	s_waitcnt lgkmcnt(4)
	v_mfma_f32_16x16x32_bf16 v[56:59], v[218:221], v[214:217], v[56:59]
	s_waitcnt lgkmcnt(3)
	v_mfma_f32_16x16x32_bf16 v[60:63], v[226:229], v[214:217], v[60:63]
	s_waitcnt lgkmcnt(2)
	v_mfma_f32_16x16x32_bf16 v[64:67], v[230:233], v[214:217], v[64:67]
	s_waitcnt lgkmcnt(1)
	v_mfma_f32_16x16x32_bf16 v[100:103], v[194:197], v[214:217], v[100:103]
	s_waitcnt lgkmcnt(0)
	v_mfma_f32_16x16x32_bf16 v[104:107], v[202:205], v[214:217], v[52:55]
	ds_read_b128 v[166:169], v78 offset:192
	ds_read_b128 v[206:209], v79 offset:35008
	ds_read_b128 v[210:213], v79 offset:39360
	ds_read_b128 v[222:225], v79 offset:43712
	ds_read_b128 v[198:201], v79 offset:48064
	ds_read_b128 v[218:221], v79 offset:52416
	ds_read_b128 v[226:229], v79 offset:56768
	ds_read_b128 v[230:233], v131
	ds_read_b128 v[194:197], v132
	ds_read_b128 v[202:205], v133
	ds_read_b128 v[214:217], v134
	s_nop 1
	v_mov_b32_e32 v3, v130
	s_waitcnt lgkmcnt(9)
	v_mfma_f32_16x16x32_bf16 v[174:177], v[206:209], v[166:169], v[48:51]
	ds_read_b128 v[206:209], v135
	s_nop 2
	s_waitcnt lgkmcnt(9)
	v_mfma_f32_16x16x32_bf16 v[178:181], v[210:213], v[166:169], v[56:59]
	ds_read_b128 v[210:213], v136
	s_waitcnt lgkmcnt(9)
	v_mfma_f32_16x16x32_bf16 v[182:185], v[222:225], v[166:169], v[60:63]
	ds_read_b128 v[222:225], v137
	s_waitcnt lgkmcnt(9)
	v_mfma_f32_16x16x32_bf16 v[186:189], v[198:201], v[166:169], v[64:67]
	ds_read_b128 v[198:201], v138
	s_waitcnt lgkmcnt(9)
	v_mfma_f32_16x16x32_bf16 v[52:55], v[218:221], v[166:169], v[100:103]
	ds_read_b128 v[218:221], v139
	s_waitcnt lgkmcnt(9)
	v_mfma_f32_16x16x32_bf16 v[48:51], v[226:229], v[166:169], v[104:107]
	ds_read_b128 v[226:229], v140
	s_waitcnt lgkmcnt(9)
	v_sub_f32_e32 v0, v75, v230
	v_sub_f32_e32 v1, v75, v231
	v_sub_f32_e32 v56, v75, v232
	v_sub_f32_e32 v57, v75, v233
	ds_read_b128 v[230:233], v141
	v_mul_f32_e32 v0, 0x3fb8aa3b, v0
	v_mul_f32_e32 v1, 0x3fb8aa3b, v1
	v_mul_f32_e32 v56, 0x3fb8aa3b, v56
	v_mul_f32_e32 v57, 0x3fb8aa3b, v57
	v_exp_f32_e32 v0, v0
	v_exp_f32_e32 v1, v1
	v_exp_f32_e32 v56, v56
	v_exp_f32_e32 v57, v57
	v_pk_mul_f32 v[0:1], v[174:175], v[0:1]
	s_waitcnt lgkmcnt(9)
	v_pk_mul_f32 v[0:1], v[194:195], v[0:1]
	v_pk_mul_f32 v[56:57], v[176:177], v[56:57]
	s_nop 0
	v_pk_mul_f32 v[56:57], v[196:197], v[56:57]
	ds_read_b128 v[194:197], v142
	s_waitcnt lgkmcnt(9)
	v_sub_f32_e32 v58, v75, v202
	v_sub_f32_e32 v59, v75, v203
	v_sub_f32_e32 v60, v75, v204
	v_sub_f32_e32 v61, v75, v205
	v_mul_f32_e32 v58, 0x3fb8aa3b, v58
	v_mul_f32_e32 v59, 0x3fb8aa3b, v59
	v_mul_f32_e32 v60, 0x3fb8aa3b, v60
	v_mul_f32_e32 v61, 0x3fb8aa3b, v61
	v_exp_f32_e32 v58, v58
	v_exp_f32_e32 v59, v59
	v_exp_f32_e32 v60, v60
	v_exp_f32_e32 v61, v61
	v_pk_mul_f32 v[58:59], v[178:179], v[58:59]
	s_waitcnt lgkmcnt(8)
	v_pk_mul_f32 v[58:59], v[214:215], v[58:59]
	v_pk_mul_f32 v[60:61], v[180:181], v[60:61]
	s_nop 0
	v_pk_mul_f32 v[60:61], v[216:217], v[60:61]
	s_waitcnt lgkmcnt(7)
	v_sub_f32_e32 v62, v75, v206
	v_sub_f32_e32 v63, v75, v207
	v_sub_f32_e32 v64, v75, v208
	v_sub_f32_e32 v65, v75, v209
	v_mul_f32_e32 v62, 0x3fb8aa3b, v62
	v_mul_f32_e32 v63, 0x3fb8aa3b, v63
	v_mul_f32_e32 v64, 0x3fb8aa3b, v64
	v_mul_f32_e32 v65, 0x3fb8aa3b, v65
	v_exp_f32_e32 v62, v62
	v_exp_f32_e32 v63, v63
	v_exp_f32_e32 v64, v64
	v_exp_f32_e32 v65, v65
	v_pk_mul_f32 v[62:63], v[182:183], v[62:63]
	s_waitcnt lgkmcnt(6)
	v_pk_mul_f32 v[62:63], v[210:211], v[62:63]
	v_pk_mul_f32 v[64:65], v[184:185], v[64:65]
	s_nop 0
	v_pk_mul_f32 v[64:65], v[212:213], v[64:65]
	s_waitcnt lgkmcnt(5)
	v_sub_f32_e32 v66, v75, v222
	v_sub_f32_e32 v67, v75, v223
	v_sub_f32_e32 v100, v75, v224
	v_sub_f32_e32 v101, v75, v225
	v_mul_f32_e32 v66, 0x3fb8aa3b, v66
	v_mul_f32_e32 v67, 0x3fb8aa3b, v67
	v_mul_f32_e32 v100, 0x3fb8aa3b, v100
	v_mul_f32_e32 v101, 0x3fb8aa3b, v101
	v_exp_f32_e32 v66, v66
	v_exp_f32_e32 v67, v67
	v_exp_f32_e32 v100, v100
	v_exp_f32_e32 v101, v101
	v_pk_mul_f32 v[66:67], v[186:187], v[66:67]
	s_waitcnt lgkmcnt(4)
	v_pk_mul_f32 v[66:67], v[198:199], v[66:67]
	v_pk_mul_f32 v[100:101], v[188:189], v[100:101]
	s_nop 0
	v_pk_mul_f32 v[108:109], v[200:201], v[100:101]
	s_waitcnt lgkmcnt(3)
	v_sub_f32_e32 v100, v75, v218
	v_sub_f32_e32 v101, v75, v219
	v_mul_f32_e32 v100, 0x3fb8aa3b, v100
	v_mul_f32_e32 v101, 0x3fb8aa3b, v101
	v_exp_f32_e32 v100, v100
	v_exp_f32_e32 v101, v101
	s_nop 0
	v_pk_mul_f32 v[52:53], v[52:53], v[100:101]
	v_sub_f32_e32 v100, v75, v220
	v_sub_f32_e32 v101, v75, v221
	v_mul_f32_e32 v100, 0x3fb8aa3b, v100
	v_mul_f32_e32 v101, 0x3fb8aa3b, v101
	v_exp_f32_e32 v100, v100
	v_exp_f32_e32 v101, v101
	s_waitcnt lgkmcnt(2)
	v_pk_mul_f32 v[52:53], v[226:227], v[52:53]
	v_pk_mul_f32 v[54:55], v[54:55], v[100:101]
	s_nop 0
	v_pk_mul_f32 v[166:167], v[228:229], v[54:55]
	s_waitcnt lgkmcnt(1)
	v_sub_f32_e32 v54, v75, v230
	v_sub_f32_e32 v55, v75, v231
	v_mul_f32_e32 v54, 0x3fb8aa3b, v54
	v_mul_f32_e32 v55, 0x3fb8aa3b, v55
	v_exp_f32_e32 v54, v54
	v_exp_f32_e32 v55, v55
	s_nop 0
	v_pk_mul_f32 v[48:49], v[48:49], v[54:55]
	s_waitcnt lgkmcnt(0)
	v_pk_mul_f32 v[104:105], v[194:195], v[48:49]
	v_sub_f32_e32 v48, v75, v232
	v_sub_f32_e32 v49, v75, v233
	v_mul_f32_e32 v48, 0x3fb8aa3b, v48
	v_mul_f32_e32 v49, 0x3fb8aa3b, v49
	v_exp_f32_e32 v48, v48
	v_exp_f32_e32 v49, v49
	s_nop 0
	v_pk_mul_f32 v[48:49], v[50:51], v[48:49]
	s_nop 0
	v_pk_mul_f32 v[106:107], v[196:197], v[48:49]
	v_cvt_pk_bf16_f32 v0, v0, v1
	v_cmp_lt_i32_e32 vcc, -1, v3
	s_nop 1
	v_cndmask_b32_e32 v1, 0, v0, vcc
	v_lshrrev_b32_e32 v0, 16, v0
	v_cmp_lt_i32_e32 vcc, 0, v3
	s_nop 1
	v_cndmask_b32_e32 v0, 0, v0, vcc
	v_perm_b32 v48, v0, v1, s69
	v_cvt_pk_bf16_f32 v0, v56, v57
	v_cmp_lt_i32_e32 vcc, 1, v3
	s_nop 1
	v_cndmask_b32_e32 v1, 0, v0, vcc
	v_lshrrev_b32_e32 v0, 16, v0
	v_cmp_lt_i32_e32 vcc, 2, v3
	s_nop 1
	v_cndmask_b32_e32 v0, 0, v0, vcc
	v_perm_b32 v49, v0, v1, s69
	v_cvt_pk_bf16_f32 v0, v58, v59
	v_cmp_lt_i32_e32 vcc, 15, v3
	s_nop 1
	v_cndmask_b32_e32 v1, 0, v0, vcc
	v_lshrrev_b32_e32 v0, 16, v0
	v_cmp_lt_i32_e32 vcc, 16, v3
	s_nop 1
	v_cndmask_b32_e32 v0, 0, v0, vcc
	v_perm_b32 v50, v0, v1, s69
	v_add_u32_e32 v1, v145, v146
	v_cvt_pk_bf16_f32 v0, v60, v61
	ds_read_b64_tr_b16 v[56:57], v1 offset:1280
	ds_read_b64_tr_b16 v[54:55], v1
	ds_read_b64_tr_b16 v[60:61], v1 offset:1312
	ds_read_b64_tr_b16 v[58:59], v1 offset:32
	v_cmp_lt_i32_e32 vcc, 17, v3
	s_nop 1
	v_cndmask_b32_e32 v51, 0, v0, vcc
	v_lshrrev_b32_e32 v0, 16, v0
	v_cmp_lt_i32_e32 vcc, 18, v3
	s_nop 1
	v_cndmask_b32_e32 v0, 0, v0, vcc
	v_perm_b32 v51, v0, v51, s69
	s_nop 0
	s_waitcnt lgkmcnt(2)
	v_mfma_f32_16x16x32_bf16 v[54:57], v[54:57], v[48:51], 0
	s_waitcnt lgkmcnt(0)
	v_mfma_f32_16x16x32_bf16 v[48:51], v[58:61], v[48:51], 0
	v_cvt_pk_bf16_f32 v0, v62, v63
	v_cmp_lt_i32_e32 vcc, 31, v3
	s_nop 1
	v_cndmask_b32_e32 v58, 0, v0, vcc
	v_lshrrev_b32_e32 v0, 16, v0
	v_cmp_lt_i32_e32 vcc, 32, v3
	s_nop 1
	v_cndmask_b32_e32 v0, 0, v0, vcc
	v_perm_b32 v58, v0, v58, s69
	v_cvt_pk_bf16_f32 v0, v64, v65
	v_cmp_lt_i32_e32 vcc, 33, v3
	ds_read_b64_tr_b16 v[64:65], v1 offset:3840
	ds_read_b64_tr_b16 v[62:63], v1 offset:2560
	ds_read_b64_tr_b16 v[100:101], v1 offset:2592
	v_cndmask_b32_e32 v59, 0, v0, vcc
	v_lshrrev_b32_e32 v0, 16, v0
	v_cmp_lt_i32_e32 vcc, 34, v3
	ds_read_b64_tr_b16 v[102:103], v1 offset:3872
	s_nop 0
	v_cndmask_b32_e32 v0, 0, v0, vcc
	v_perm_b32 v59, v0, v59, s69
	v_cvt_pk_bf16_f32 v0, v66, v67
	v_cmp_lt_i32_e32 vcc, 47, v3
	s_nop 1
	v_cndmask_b32_e32 v60, 0, v0, vcc
	v_lshrrev_b32_e32 v0, 16, v0
	v_cmp_lt_i32_e32 vcc, 48, v3
	s_nop 1
	v_cndmask_b32_e32 v0, 0, v0, vcc
	v_perm_b32 v60, v0, v60, s69
	v_cvt_pk_bf16_f32 v0, v108, v109
	v_cmp_lt_i32_e32 vcc, 49, v3
	s_nop 1
	v_cndmask_b32_e32 v61, 0, v0, vcc
	v_lshrrev_b32_e32 v0, 16, v0
	v_cmp_lt_i32_e32 vcc, 50, v3
	s_nop 1
	v_cndmask_b32_e32 v0, 0, v0, vcc
	v_perm_b32 v61, v0, v61, s69
	s_nop 0
	s_waitcnt lgkmcnt(2)
	v_mfma_f32_16x16x32_bf16 v[54:57], v[62:65], v[58:61], v[54:57]
	s_waitcnt lgkmcnt(0)
	v_mfma_f32_16x16x32_bf16 v[58:61], v[100:103], v[58:61], v[48:51]
	v_cvt_pk_bf16_f32 v0, v52, v53
	v_cmp_lt_i32_e32 vcc, 63, v3
	s_nop 1
	v_cndmask_b32_e32 v48, 0, v0, vcc
	v_lshrrev_b32_e32 v0, 16, v0
	v_cmp_lt_i32_e32 vcc, 64, v3
	s_nop 1
	v_cndmask_b32_e32 v0, 0, v0, vcc
	v_perm_b32 v62, v0, v48, s69
	v_cvt_pk_bf16_f32 v0, v166, v167
	v_cmp_lt_i32_e32 vcc, s86, v3
	s_nop 1
	v_cndmask_b32_e32 v48, 0, v0, vcc
	v_lshrrev_b32_e32 v0, 16, v0
	v_cmp_lt_i32_e32 vcc, s88, v3
	s_nop 1
	v_cndmask_b32_e32 v0, 0, v0, vcc
	v_perm_b32 v63, v0, v48, s69
	v_cvt_pk_bf16_f32 v0, v104, v105
	v_cmp_lt_i32_e32 vcc, s52, v3
	s_nop 1
	v_cndmask_b32_e32 v48, 0, v0, vcc
	v_lshrrev_b32_e32 v0, 16, v0
	v_cmp_lt_i32_e32 vcc, s97, v3
	s_nop 1
	v_cndmask_b32_e32 v0, 0, v0, vcc
	v_perm_b32 v64, v0, v48, s69
	v_cvt_pk_bf16_f32 v0, v106, v107
	v_cmp_lt_i32_e32 vcc, s53, v3
	s_nop 1
	v_cndmask_b32_e32 v48, 0, v0, vcc
	v_lshrrev_b32_e32 v0, 16, v0
	v_cmp_lt_i32_e32 vcc, s54, v3
	s_nop 1
	v_cndmask_b32_e32 v0, 0, v0, vcc
	v_perm_b32 v65, v0, v48, s69
	ds_read_b64_tr_b16 v[50:51], v1 offset:6400
	ds_read_b64_tr_b16 v[48:49], v1 offset:5120
	ds_read_b64_tr_b16 v[52:53], v1 offset:5152
	s_waitcnt lgkmcnt(1)
	v_mfma_f32_16x16x32_bf16 v[48:51], v[48:51], v[62:65], v[54:57]
	s_nop 2
	ds_read_b64_tr_b16 v[54:55], v1 offset:6432
	s_waitcnt lgkmcnt(0)
	v_mfma_f32_16x16x32_bf16 v[52:55], v[52:55], v[62:65], v[58:61]

.LBB0_490:
	s_cmp_gt_i32 s64, 3
	s_mov_b64 s[84:85], -1
	s_cbranch_scc0 .LBB0_492
	ds_read_b128 v[194:197], v79 offset:34816
	ds_read_b128 v[198:201], v79 offset:39168
	ds_read_b128 v[202:205], v78
	ds_read_b128 v[206:209], v79 offset:52224
	ds_read_b128 v[210:213], v79 offset:43520
	ds_read_b128 v[214:217], v79 offset:47872
	ds_read_b128 v[218:221], v78 offset:64
	ds_read_b128 v[222:225], v79 offset:34880
	ds_read_b128 v[226:229], v79 offset:39232
	ds_read_b128 v[230:233], v79 offset:43584
	s_waitcnt lgkmcnt(7)
	v_mfma_f32_16x16x32_bf16 v[48:51], v[194:197], v[202:205], 0
	ds_read_b128 v[194:197], v79 offset:47936
	v_mfma_f32_16x16x32_bf16 v[52:55], v[198:201], v[202:205], 0
	ds_read_b128 v[198:201], v79 offset:52288
	s_waitcnt lgkmcnt(7)
	v_mfma_f32_16x16x32_bf16 v[64:67], v[210:213], v[202:205], 0
	ds_read_b128 v[210:213], v78 offset:128
	s_waitcnt lgkmcnt(7)
	v_mfma_f32_16x16x32_bf16 v[100:103], v[214:217], v[202:205], 0
	ds_read_b128 v[214:217], v79 offset:34944
	v_mfma_f32_16x16x32_bf16 v[56:59], v[206:209], v[202:205], 0
	ds_read_b128 v[202:205], v79 offset:39296
	ds_read_b128 v[206:209], v79 offset:43648
	s_waitcnt lgkmcnt(8)
	v_mfma_f32_16x16x32_bf16 v[48:51], v[222:225], v[218:221], v[48:51]
	ds_read_b128 v[222:225], v79 offset:48000
	s_waitcnt lgkmcnt(8)
	v_mfma_f32_16x16x32_bf16 v[52:55], v[226:229], v[218:221], v[52:55]
	ds_read_b128 v[226:229], v79 offset:52352
	s_waitcnt lgkmcnt(8)
	v_mfma_f32_16x16x32_bf16 v[64:67], v[230:233], v[218:221], v[64:67]
	ds_read_b128 v[230:233], v78 offset:192
	s_waitcnt lgkmcnt(8)
	v_mfma_f32_16x16x32_bf16 v[100:103], v[194:197], v[218:221], v[100:103]
	ds_read_b128 v[194:197], v79 offset:35008
	s_waitcnt lgkmcnt(8)
	v_mfma_f32_16x16x32_bf16 v[56:59], v[198:201], v[218:221], v[56:59]
	ds_read_b128 v[198:201], v79 offset:39360
	ds_read_b128 v[218:221], v79 offset:43712
	s_waitcnt lgkmcnt(8)
	v_mfma_f32_16x16x32_bf16 v[48:51], v[214:217], v[210:213], v[48:51]
	ds_read_b128 v[214:217], v79 offset:48064
	s_waitcnt lgkmcnt(8)
	v_mfma_f32_16x16x32_bf16 v[52:55], v[202:205], v[210:213], v[52:55]
	ds_read_b128 v[202:205], v79 offset:52416
	s_waitcnt lgkmcnt(8)
	v_mfma_f32_16x16x32_bf16 v[64:67], v[206:209], v[210:213], v[64:67]
	ds_read_b128 v[206:209], v131
	s_waitcnt lgkmcnt(8)
	v_mfma_f32_16x16x32_bf16 v[100:103], v[222:225], v[210:213], v[100:103]
	ds_read_b128 v[222:225], v132
	s_waitcnt lgkmcnt(8)
	v_mfma_f32_16x16x32_bf16 v[56:59], v[226:229], v[210:213], v[56:59]
	ds_read_b128 v[210:213], v133
	ds_read_b128 v[226:229], v134
	v_mov_b32_e32 v3, v130
	s_waitcnt lgkmcnt(8)
	v_mfma_f32_16x16x32_bf16 v[104:107], v[194:197], v[230:233], v[48:51]
	ds_read_b128 v[194:197], v135
	s_nop 2
	s_waitcnt lgkmcnt(8)
	v_mfma_f32_16x16x32_bf16 v[166:169], v[198:201], v[230:233], v[52:55]
	ds_read_b128 v[198:201], v136
	s_waitcnt lgkmcnt(8)
	v_mfma_f32_16x16x32_bf16 v[64:67], v[218:221], v[230:233], v[64:67]
	ds_read_b128 v[218:221], v137
	s_waitcnt lgkmcnt(8)
	v_mfma_f32_16x16x32_bf16 v[52:55], v[214:217], v[230:233], v[100:103]
	ds_read_b128 v[214:217], v138
	s_waitcnt lgkmcnt(8)
	v_mfma_f32_16x16x32_bf16 v[48:51], v[202:205], v[230:233], v[56:59]
	ds_read_b128 v[202:205], v139
	ds_read_b128 v[230:233], v140
	s_nop 2
	s_waitcnt lgkmcnt(9)
	v_sub_f32_e32 v0, v75, v206
	v_sub_f32_e32 v1, v75, v207
	v_mul_f32_e32 v0, 0x3fb8aa3b, v0
	v_mul_f32_e32 v1, 0x3fb8aa3b, v1
	v_exp_f32_e32 v0, v0
	v_exp_f32_e32 v1, v1
	v_sub_f32_e32 v56, v75, v208
	v_sub_f32_e32 v57, v75, v209
	v_mul_f32_e32 v56, 0x3fb8aa3b, v56
	v_pk_mul_f32 v[0:1], v[104:105], v[0:1]
	v_mul_f32_e32 v57, 0x3fb8aa3b, v57
	s_waitcnt lgkmcnt(8)
	v_pk_mul_f32 v[0:1], v[222:223], v[0:1]
	v_exp_f32_e32 v56, v56
	v_exp_f32_e32 v57, v57
	s_waitcnt lgkmcnt(7)
	v_sub_f32_e32 v58, v75, v210
	v_sub_f32_e32 v59, v75, v211
	v_mul_f32_e32 v58, 0x3fb8aa3b, v58
	v_mul_f32_e32 v59, 0x3fb8aa3b, v59
	v_exp_f32_e32 v58, v58
	v_exp_f32_e32 v59, v59
	v_pk_mul_f32 v[56:57], v[106:107], v[56:57]
	v_pk_mul_f32 v[58:59], v[166:167], v[58:59]
	s_waitcnt lgkmcnt(6)
	v_pk_mul_f32 v[104:105], v[226:227], v[58:59]
	v_sub_f32_e32 v58, v75, v212
	v_sub_f32_e32 v59, v75, v213
	v_mul_f32_e32 v58, 0x3fb8aa3b, v58
	v_mul_f32_e32 v59, 0x3fb8aa3b, v59
	v_exp_f32_e32 v58, v58
	v_exp_f32_e32 v59, v59
	v_pk_mul_f32 v[56:57], v[224:225], v[56:57]
	v_pk_mul_f32 v[58:59], v[168:169], v[58:59]
	s_nop 0
	v_pk_mul_f32 v[106:107], v[228:229], v[58:59]
	s_waitcnt lgkmcnt(5)
	v_sub_f32_e32 v58, v75, v194
	v_sub_f32_e32 v59, v75, v195
	v_mul_f32_e32 v58, 0x3fb8aa3b, v58
	v_mul_f32_e32 v59, 0x3fb8aa3b, v59
	v_exp_f32_e32 v58, v58
	v_exp_f32_e32 v59, v59
	s_nop 0
	v_pk_mul_f32 v[58:59], v[64:65], v[58:59]
	s_waitcnt lgkmcnt(4)
	v_pk_mul_f32 v[100:101], v[198:199], v[58:59]
	v_sub_f32_e32 v58, v75, v196
	v_sub_f32_e32 v59, v75, v197
	v_mul_f32_e32 v58, 0x3fb8aa3b, v58
	v_mul_f32_e32 v59, 0x3fb8aa3b, v59
	v_exp_f32_e32 v58, v58
	v_exp_f32_e32 v59, v59
	s_nop 0
	v_pk_mul_f32 v[58:59], v[66:67], v[58:59]
	s_nop 0
	v_pk_mul_f32 v[66:67], v[200:201], v[58:59]
	s_waitcnt lgkmcnt(3)
	v_sub_f32_e32 v58, v75, v218
	v_sub_f32_e32 v59, v75, v219
	v_mul_f32_e32 v58, 0x3fb8aa3b, v58
	v_mul_f32_e32 v59, 0x3fb8aa3b, v59
	v_exp_f32_e32 v58, v58
	v_exp_f32_e32 v59, v59
	s_nop 0
	v_pk_mul_f32 v[52:53], v[52:53], v[58:59]
	s_waitcnt lgkmcnt(2)
	v_pk_mul_f32 v[62:63], v[214:215], v[52:53]
	v_sub_f32_e32 v52, v75, v220
	v_sub_f32_e32 v53, v75, v221
	v_mul_f32_e32 v52, 0x3fb8aa3b, v52
	v_mul_f32_e32 v53, 0x3fb8aa3b, v53
	v_exp_f32_e32 v52, v52
	v_exp_f32_e32 v53, v53
	s_nop 0
	v_pk_mul_f32 v[52:53], v[54:55], v[52:53]
	s_nop 0
	v_pk_mul_f32 v[64:65], v[216:217], v[52:53]
	s_waitcnt lgkmcnt(1)
	v_sub_f32_e32 v52, v75, v202
	v_sub_f32_e32 v53, v75, v203
	v_mul_f32_e32 v52, 0x3fb8aa3b, v52
	v_mul_f32_e32 v53, 0x3fb8aa3b, v53
	v_exp_f32_e32 v52, v52
	v_exp_f32_e32 v53, v53
	s_nop 0
	v_pk_mul_f32 v[48:49], v[48:49], v[52:53]
	s_waitcnt lgkmcnt(0)
	v_pk_mul_f32 v[102:103], v[230:231], v[48:49]
	v_sub_f32_e32 v48, v75, v204
	v_sub_f32_e32 v49, v75, v205
	v_mul_f32_e32 v48, 0x3fb8aa3b, v48
	v_mul_f32_e32 v49, 0x3fb8aa3b, v49
	v_exp_f32_e32 v48, v48
	v_exp_f32_e32 v49, v49
	s_nop 0
	v_pk_mul_f32 v[48:49], v[50:51], v[48:49]
	s_nop 0
	v_pk_mul_f32 v[108:109], v[232:233], v[48:49]
	v_cvt_pk_bf16_f32 v0, v0, v1
	v_cmp_lt_i32_e32 vcc, -1, v3
	s_nop 1
	v_cndmask_b32_e32 v1, 0, v0, vcc
	v_lshrrev_b32_e32 v0, 16, v0
	v_cmp_lt_i32_e32 vcc, 0, v3
	s_nop 1
	v_cndmask_b32_e32 v0, 0, v0, vcc
	v_perm_b32 v48, v0, v1, s69
	v_cvt_pk_bf16_f32 v0, v56, v57
	v_cmp_lt_i32_e32 vcc, 1, v3
	s_nop 1
	v_cndmask_b32_e32 v1, 0, v0, vcc
	v_lshrrev_b32_e32 v0, 16, v0
	v_cmp_lt_i32_e32 vcc, 2, v3
	s_nop 1
	v_cndmask_b32_e32 v0, 0, v0, vcc
	v_perm_b32 v49, v0, v1, s69
	v_cvt_pk_bf16_f32 v0, v104, v105
	v_cmp_lt_i32_e32 vcc, 15, v3
	v_add_u32_e32 v104, v145, v146
	ds_read_b64_tr_b16 v[54:55], v104 offset:1280
	ds_read_b64_tr_b16 v[52:53], v104
	v_cndmask_b32_e32 v1, 0, v0, vcc
	v_lshrrev_b32_e32 v0, 16, v0
	v_cmp_lt_i32_e32 vcc, 16, v3
	ds_read_b64_tr_b16 v[58:59], v104 offset:1312
	ds_read_b64_tr_b16 v[56:57], v104 offset:32
	v_cndmask_b32_e32 v0, 0, v0, vcc
	v_perm_b32 v50, v0, v1, s69
	v_cvt_pk_bf16_f32 v0, v106, v107
	v_cmp_lt_i32_e32 vcc, 17, v3
	s_nop 1
	v_cndmask_b32_e32 v1, 0, v0, vcc
	v_lshrrev_b32_e32 v0, 16, v0
	v_cmp_lt_i32_e32 vcc, 18, v3
	s_nop 1
	v_cndmask_b32_e32 v0, 0, v0, vcc
	v_perm_b32 v51, v0, v1, s69
	s_nop 0
	s_waitcnt lgkmcnt(2)
	v_mfma_f32_16x16x32_bf16 v[52:55], v[52:55], v[48:51], 0
	s_waitcnt lgkmcnt(0)
	v_mfma_f32_16x16x32_bf16 v[48:51], v[56:59], v[48:51], 0
	v_cvt_pk_bf16_f32 v0, v100, v101
	v_cmp_lt_i32_e32 vcc, 31, v3
	s_nop 1
	v_cndmask_b32_e32 v1, 0, v0, vcc
	v_lshrrev_b32_e32 v0, 16, v0
	v_cmp_lt_i32_e32 vcc, 32, v3
	s_nop 1
	v_cndmask_b32_e32 v0, 0, v0, vcc
	v_perm_b32 v56, v0, v1, s69
	v_cvt_pk_bf16_f32 v0, v66, v67
	v_cmp_lt_i32_e32 vcc, 33, v3
	s_nop 1
	v_cndmask_b32_e32 v1, 0, v0, vcc
	v_lshrrev_b32_e32 v0, 16, v0
	v_cmp_lt_i32_e32 vcc, 34, v3
	s_nop 1
	v_cndmask_b32_e32 v0, 0, v0, vcc
	v_perm_b32 v57, v0, v1, s69
	v_cvt_pk_bf16_f32 v0, v62, v63
	v_cmp_lt_i32_e32 vcc, 47, v3
	s_nop 1
	v_cndmask_b32_e32 v1, 0, v0, vcc
	v_lshrrev_b32_e32 v0, 16, v0
	v_cmp_lt_i32_e32 vcc, 48, v3
	s_nop 1
	v_cndmask_b32_e32 v0, 0, v0, vcc
	v_perm_b32 v58, v0, v1, s69
	v_cvt_pk_bf16_f32 v0, v64, v65
	ds_read_b64_tr_b16 v[62:63], v104 offset:3840
	ds_read_b64_tr_b16 v[60:61], v104 offset:2560
	ds_read_b64_tr_b16 v[64:65], v104 offset:2592
	ds_read_b64_tr_b16 v[66:67], v104 offset:3872
	v_cmp_lt_i32_e32 vcc, 49, v3
	s_nop 1
	v_cndmask_b32_e32 v1, 0, v0, vcc
	v_lshrrev_b32_e32 v0, 16, v0
	v_cmp_lt_i32_e32 vcc, 50, v3
	s_nop 1
	v_cndmask_b32_e32 v0, 0, v0, vcc
	v_perm_b32 v59, v0, v1, s69
	s_nop 0
	s_waitcnt lgkmcnt(2)
	v_mfma_f32_16x16x32_bf16 v[52:55], v[60:63], v[56:59], v[52:55]
	s_waitcnt lgkmcnt(0)
	v_mfma_f32_16x16x32_bf16 v[56:59], v[64:67], v[56:59], v[48:51]
	v_cvt_pk_bf16_f32 v0, v102, v103
	v_cmp_lt_i32_e32 vcc, 63, v3
	s_mov_b64 s[84:85], 0
	s_nop 0
	v_cndmask_b32_e32 v1, 0, v0, vcc
	v_lshrrev_b32_e32 v0, 16, v0
	v_cmp_lt_i32_e32 vcc, 64, v3
	s_nop 1
	v_cndmask_b32_e32 v0, 0, v0, vcc
	v_perm_b32 v0, v0, v1, s69
	v_cvt_pk_bf16_f32 v1, v108, v109
	v_cmp_lt_i32_e32 vcc, s86, v3
	s_nop 1
	v_cndmask_b32_e32 v48, 0, v1, vcc
	v_lshrrev_b32_e32 v1, 16, v1
	v_cmp_lt_i32_e32 vcc, s88, v3
	v_mov_b32_e32 v3, v2
	s_nop 0
	v_cndmask_b32_e32 v1, 0, v1, vcc
	v_perm_b32 v1, v1, v48, s69
	ds_read_b64_tr_b16 v[50:51], v104 offset:6400
	ds_read_b64_tr_b16 v[48:49], v104 offset:5120
	ds_read_b64_tr_b16 v[60:61], v104 offset:5152
	ds_read_b64_tr_b16 v[62:63], v104 offset:6432
	s_waitcnt lgkmcnt(2)
	v_mfma_f32_16x16x32_bf16 v[48:51], v[48:51], v[0:3], v[52:55]
	s_waitcnt lgkmcnt(0)
	v_mfma_f32_16x16x32_bf16 v[52:55], v[60:63], v[0:3], v[56:59]
.LBB0_492:
	s_andn2_b64 vcc, exec, s[84:85]
	s_cbranch_vccnz .LBB0_494
	ds_read_b128 v[194:197], v79 offset:34816
	ds_read_b128 v[198:201], v78
	ds_read_b128 v[202:205], v79 offset:39168
	ds_read_b128 v[206:209], v79 offset:43520
	ds_read_b128 v[210:213], v79 offset:47872
	ds_read_b128 v[214:217], v78 offset:64
	ds_read_b128 v[218:221], v79 offset:34880
	ds_read_b128 v[222:225], v79 offset:39232
	ds_read_b128 v[226:229], v79 offset:43584
	ds_read_b128 v[230:233], v79 offset:47936
	s_nop 3
	s_nop 0
	s_waitcnt lgkmcnt(8)
	v_mfma_f32_16x16x32_bf16 v[48:51], v[194:197], v[198:201], 0
	ds_read_b128 v[194:197], v78 offset:128
	s_waitcnt lgkmcnt(8)
	v_mfma_f32_16x16x32_bf16 v[56:59], v[202:205], v[198:201], 0
	ds_read_b128 v[202:205], v79 offset:34944
	s_waitcnt lgkmcnt(8)
	v_mfma_f32_16x16x32_bf16 v[60:63], v[206:209], v[198:201], 0
	ds_read_b128 v[206:209], v79 offset:39296
	s_waitcnt lgkmcnt(8)
	v_mfma_f32_16x16x32_bf16 v[52:55], v[210:213], v[198:201], 0
	ds_read_b128 v[198:201], v79 offset:43648
	ds_read_b128 v[210:213], v79 offset:48000
	s_waitcnt lgkmcnt(8)
	v_mfma_f32_16x16x32_bf16 v[48:51], v[218:221], v[214:217], v[48:51]
	ds_read_b128 v[218:221], v78 offset:192
	s_waitcnt lgkmcnt(8)
	v_mfma_f32_16x16x32_bf16 v[56:59], v[222:225], v[214:217], v[56:59]
	ds_read_b128 v[222:225], v79 offset:35008
	s_waitcnt lgkmcnt(8)
	v_mfma_f32_16x16x32_bf16 v[60:63], v[226:229], v[214:217], v[60:63]
	ds_read_b128 v[226:229], v79 offset:39360
	s_waitcnt lgkmcnt(8)
	v_mfma_f32_16x16x32_bf16 v[52:55], v[230:233], v[214:217], v[52:55]
	ds_read_b128 v[214:217], v79 offset:43712
	ds_read_b128 v[230:233], v79 offset:48064
	s_waitcnt lgkmcnt(8)
	v_mfma_f32_16x16x32_bf16 v[48:51], v[202:205], v[194:197], v[48:51]
	ds_read_b128 v[202:205], v131
	s_waitcnt lgkmcnt(8)
	v_mfma_f32_16x16x32_bf16 v[56:59], v[206:209], v[194:197], v[56:59]
	ds_read_b128 v[206:209], v132
	s_waitcnt lgkmcnt(8)
	v_mfma_f32_16x16x32_bf16 v[60:63], v[198:201], v[194:197], v[60:63]
	ds_read_b128 v[198:201], v133
	s_waitcnt lgkmcnt(8)
	v_mfma_f32_16x16x32_bf16 v[52:55], v[210:213], v[194:197], v[52:55]
	ds_read_b128 v[194:197], v134
	ds_read_b128 v[210:213], v135
	v_mov_b32_e32 v3, v130
	s_waitcnt lgkmcnt(8)
	v_mfma_f32_16x16x32_bf16 v[48:51], v[222:225], v[218:221], v[48:51]
	ds_read_b128 v[222:225], v136
	s_waitcnt lgkmcnt(8)
	v_mfma_f32_16x16x32_bf16 v[56:59], v[226:229], v[218:221], v[56:59]
	ds_read_b128 v[226:229], v137
	s_waitcnt lgkmcnt(8)
	v_mfma_f32_16x16x32_bf16 v[60:63], v[214:217], v[218:221], v[60:63]
	ds_read_b128 v[214:217], v138
	s_waitcnt lgkmcnt(8)
	v_mfma_f32_16x16x32_bf16 v[52:55], v[230:233], v[218:221], v[52:55]
	s_waitcnt lgkmcnt(7)
	v_sub_f32_e32 v0, v75, v202
	v_sub_f32_e32 v1, v75, v203
	v_mul_f32_e32 v0, 0x3fb8aa3b, v0
	v_mul_f32_e32 v1, 0x3fb8aa3b, v1
	v_exp_f32_e32 v0, v0
	v_exp_f32_e32 v1, v1
	s_nop 0
	v_pk_mul_f32 v[0:1], v[48:49], v[0:1]
	v_sub_f32_e32 v48, v75, v204
	v_sub_f32_e32 v49, v75, v205
	v_mul_f32_e32 v48, 0x3fb8aa3b, v48
	v_mul_f32_e32 v49, 0x3fb8aa3b, v49
	v_exp_f32_e32 v48, v48
	v_exp_f32_e32 v49, v49
	s_waitcnt lgkmcnt(6)
	v_pk_mul_f32 v[0:1], v[206:207], v[0:1]
	v_pk_mul_f32 v[48:49], v[50:51], v[48:49]
	s_nop 0
	v_pk_mul_f32 v[100:101], v[208:209], v[48:49]
	s_waitcnt lgkmcnt(5)
	v_sub_f32_e32 v48, v75, v198
	v_sub_f32_e32 v49, v75, v199
	v_mul_f32_e32 v48, 0x3fb8aa3b, v48
	v_mul_f32_e32 v49, 0x3fb8aa3b, v49
	v_exp_f32_e32 v48, v48
	v_exp_f32_e32 v49, v49
	s_nop 0
	v_pk_mul_f32 v[48:49], v[56:57], v[48:49]
	s_waitcnt lgkmcnt(4)
	v_pk_mul_f32 v[64:65], v[194:195], v[48:49]
	v_sub_f32_e32 v48, v75, v200
	v_sub_f32_e32 v49, v75, v201
	v_mul_f32_e32 v48, 0x3fb8aa3b, v48
	v_mul_f32_e32 v49, 0x3fb8aa3b, v49
	v_exp_f32_e32 v48, v48
	v_exp_f32_e32 v49, v49
	s_nop 0
	v_pk_mul_f32 v[48:49], v[58:59], v[48:49]
	s_nop 0
	v_pk_mul_f32 v[66:67], v[196:197], v[48:49]
	s_waitcnt lgkmcnt(3)
	v_sub_f32_e32 v48, v75, v210
	v_sub_f32_e32 v49, v75, v211
	v_mul_f32_e32 v48, 0x3fb8aa3b, v48
	v_mul_f32_e32 v49, 0x3fb8aa3b, v49
	v_exp_f32_e32 v48, v48
	v_exp_f32_e32 v49, v49
	s_nop 0
	v_pk_mul_f32 v[48:49], v[60:61], v[48:49]
	s_waitcnt lgkmcnt(2)
	v_pk_mul_f32 v[60:61], v[222:223], v[48:49]
	v_sub_f32_e32 v48, v75, v212
	v_sub_f32_e32 v49, v75, v213
	v_mul_f32_e32 v48, 0x3fb8aa3b, v48
	v_mul_f32_e32 v49, 0x3fb8aa3b, v49
	v_exp_f32_e32 v48, v48
	v_exp_f32_e32 v49, v49
	s_nop 0
	v_pk_mul_f32 v[48:49], v[62:63], v[48:49]
	s_nop 0
	v_pk_mul_f32 v[62:63], v[224:225], v[48:49]
	s_waitcnt lgkmcnt(1)
	v_sub_f32_e32 v48, v75, v226
	v_sub_f32_e32 v49, v75, v227
	v_mul_f32_e32 v48, 0x3fb8aa3b, v48
	v_mul_f32_e32 v49, 0x3fb8aa3b, v49
	v_exp_f32_e32 v48, v48
	v_exp_f32_e32 v49, v49
	s_nop 0
	v_pk_mul_f32 v[48:49], v[52:53], v[48:49]
	s_waitcnt lgkmcnt(0)
	v_pk_mul_f32 v[102:103], v[214:215], v[48:49]
	v_sub_f32_e32 v48, v75, v228
	v_sub_f32_e32 v49, v75, v229
	v_mul_f32_e32 v48, 0x3fb8aa3b, v48
	v_mul_f32_e32 v49, 0x3fb8aa3b, v49
	v_exp_f32_e32 v48, v48
	v_exp_f32_e32 v49, v49
	s_nop 0
	v_pk_mul_f32 v[48:49], v[54:55], v[48:49]
	s_nop 0
	v_pk_mul_f32 v[104:105], v[216:217], v[48:49]
	v_cvt_pk_bf16_f32 v0, v0, v1
	v_cmp_lt_i32_e32 vcc, -1, v3
	s_nop 1
	v_cndmask_b32_e32 v1, 0, v0, vcc
	v_lshrrev_b32_e32 v0, 16, v0
	v_cmp_lt_i32_e32 vcc, 0, v3
	s_nop 1
	v_cndmask_b32_e32 v0, 0, v0, vcc
	v_perm_b32 v48, v0, v1, s69
	v_cvt_pk_bf16_f32 v0, v100, v101
	v_cmp_lt_i32_e32 vcc, 1, v3
	s_nop 1
	v_cndmask_b32_e32 v1, 0, v0, vcc
	v_lshrrev_b32_e32 v0, 16, v0
	v_cmp_lt_i32_e32 vcc, 2, v3
	s_nop 1
	v_cndmask_b32_e32 v0, 0, v0, vcc
	v_perm_b32 v49, v0, v1, s69
	v_cvt_pk_bf16_f32 v0, v64, v65
	v_cmp_lt_i32_e32 vcc, 15, v3
	s_nop 1
	v_cndmask_b32_e32 v1, 0, v0, vcc
	v_lshrrev_b32_e32 v0, 16, v0
	v_cmp_lt_i32_e32 vcc, 16, v3
	s_nop 1
	v_cndmask_b32_e32 v0, 0, v0, vcc
	v_perm_b32 v50, v0, v1, s69
	v_add_u32_e32 v1, v145, v146
	ds_read_b64_tr_b16 v[54:55], v1 offset:1280
	ds_read_b64_tr_b16 v[52:53], v1
	v_cvt_pk_bf16_f32 v0, v66, v67
	v_cmp_lt_i32_e32 vcc, 17, v3
	ds_read_b64_tr_b16 v[58:59], v1 offset:1312
	ds_read_b64_tr_b16 v[56:57], v1 offset:32
	v_cndmask_b32_e32 v51, 0, v0, vcc
	v_lshrrev_b32_e32 v0, 16, v0
	v_cmp_lt_i32_e32 vcc, 18, v3
	s_nop 1
	v_cndmask_b32_e32 v0, 0, v0, vcc
	v_perm_b32 v51, v0, v51, s69
	s_nop 0
	s_waitcnt lgkmcnt(2)
	v_mfma_f32_16x16x32_bf16 v[52:55], v[52:55], v[48:51], 0
	s_waitcnt lgkmcnt(0)
	v_mfma_f32_16x16x32_bf16 v[56:59], v[56:59], v[48:51], 0
	v_cvt_pk_bf16_f32 v0, v60, v61
	v_cmp_lt_i32_e32 vcc, 31, v3
	s_nop 1
	v_cndmask_b32_e32 v48, 0, v0, vcc
	v_lshrrev_b32_e32 v0, 16, v0
	v_cmp_lt_i32_e32 vcc, 32, v3
	s_nop 1
	v_cndmask_b32_e32 v0, 0, v0, vcc
	v_perm_b32 v60, v0, v48, s69
	v_cvt_pk_bf16_f32 v0, v62, v63
	v_cmp_lt_i32_e32 vcc, 33, v3
	s_nop 1
	v_cndmask_b32_e32 v48, 0, v0, vcc
	v_lshrrev_b32_e32 v0, 16, v0
	v_cmp_lt_i32_e32 vcc, 34, v3
	s_nop 1
	v_cndmask_b32_e32 v0, 0, v0, vcc
	v_perm_b32 v61, v0, v48, s69
	v_cvt_pk_bf16_f32 v0, v102, v103
	v_cmp_lt_i32_e32 vcc, 47, v3
	s_nop 1
	v_cndmask_b32_e32 v48, 0, v0, vcc
	v_lshrrev_b32_e32 v0, 16, v0
	v_cmp_lt_i32_e32 vcc, 48, v3
	s_nop 1
	v_cndmask_b32_e32 v0, 0, v0, vcc
	v_perm_b32 v62, v0, v48, s69
	v_cvt_pk_bf16_f32 v0, v104, v105
	v_cmp_lt_i32_e32 vcc, 49, v3
	s_nop 1
	v_cndmask_b32_e32 v48, 0, v0, vcc
	v_lshrrev_b32_e32 v0, 16, v0
	v_cmp_lt_i32_e32 vcc, 50, v3
	s_nop 1
	v_cndmask_b32_e32 v0, 0, v0, vcc
	v_perm_b32 v63, v0, v48, s69
	ds_read_b64_tr_b16 v[50:51], v1 offset:3840
	ds_read_b64_tr_b16 v[48:49], v1 offset:2560
	ds_read_b64_tr_b16 v[64:65], v1 offset:2592
	ds_read_b64_tr_b16 v[66:67], v1 offset:3872
	s_waitcnt lgkmcnt(2)
	v_mfma_f32_16x16x32_bf16 v[48:51], v[48:51], v[60:63], v[52:55]
	s_waitcnt lgkmcnt(0)
	v_mfma_f32_16x16x32_bf16 v[52:55], v[64:67], v[60:63], v[56:59]

.LBB0_504:
	s_and_b64 vcc, exec, s[30:31]
	s_cbranch_vccz .LBB0_506
	ds_read_b128 v[194:197], v79 offset:34816
	ds_read_b128 v[198:201], v78
	ds_read_b128 v[202:205], v79 offset:39168
	ds_read_b128 v[206:209], v79 offset:43520
	ds_read_b128 v[210:213], v79 offset:47872
	ds_read_b128 v[214:217], v79 offset:52224
	ds_read_b128 v[218:221], v79 offset:56576
	ds_read_b128 v[222:225], v79 offset:60928
	ds_read_b128 v[226:229], v79 offset:65280
	ds_read_b128 v[230:233], v78 offset:64
	s_nop 0
	s_nop 0
	s_waitcnt lgkmcnt(8)
	v_mfma_f32_16x16x32_bf16 v[48:51], v[194:197], v[198:201], 0
	ds_read_b128 v[194:197], v79 offset:34880
	s_waitcnt lgkmcnt(8)
	v_mfma_f32_16x16x32_bf16 v[56:59], v[202:205], v[198:201], 0
	ds_read_b128 v[202:205], v79 offset:39232
	s_waitcnt lgkmcnt(8)
	v_mfma_f32_16x16x32_bf16 v[60:63], v[206:209], v[198:201], 0
	ds_read_b128 v[206:209], v79 offset:43584
	s_waitcnt lgkmcnt(8)
	v_mfma_f32_16x16x32_bf16 v[64:67], v[210:213], v[198:201], 0
	ds_read_b128 v[210:213], v79 offset:47936
	s_waitcnt lgkmcnt(8)
	v_mfma_f32_16x16x32_bf16 v[100:103], v[214:217], v[198:201], 0
	ds_read_b128 v[214:217], v79 offset:52288
	s_waitcnt lgkmcnt(8)
	v_mfma_f32_16x16x32_bf16 v[104:107], v[218:221], v[198:201], 0
	ds_read_b128 v[218:221], v79 offset:56640
	s_waitcnt lgkmcnt(8)
	v_mfma_f32_16x16x32_bf16 v[166:169], v[222:225], v[198:201], 0
	ds_read_b128 v[222:225], v79 offset:60992
	s_waitcnt lgkmcnt(8)
	v_mfma_f32_16x16x32_bf16 v[52:55], v[226:229], v[198:201], 0
	ds_read_b128 v[198:201], v79 offset:65344
	ds_read_b128 v[226:229], v78 offset:128
	s_waitcnt lgkmcnt(8)
	v_mfma_f32_16x16x32_bf16 v[48:51], v[194:197], v[230:233], v[48:51]
	ds_read_b128 v[194:197], v79 offset:34944
	s_waitcnt lgkmcnt(8)
	v_mfma_f32_16x16x32_bf16 v[56:59], v[202:205], v[230:233], v[56:59]
	ds_read_b128 v[202:205], v79 offset:39296
	s_waitcnt lgkmcnt(8)
	v_mfma_f32_16x16x32_bf16 v[60:63], v[206:209], v[230:233], v[60:63]
	ds_read_b128 v[206:209], v79 offset:43648
	s_waitcnt lgkmcnt(8)
	v_mfma_f32_16x16x32_bf16 v[64:67], v[210:213], v[230:233], v[64:67]
	ds_read_b128 v[210:213], v79 offset:48000
	s_waitcnt lgkmcnt(8)
	v_mfma_f32_16x16x32_bf16 v[100:103], v[214:217], v[230:233], v[100:103]
	ds_read_b128 v[214:217], v79 offset:52352
	s_waitcnt lgkmcnt(8)
	v_mfma_f32_16x16x32_bf16 v[104:107], v[218:221], v[230:233], v[104:107]
	ds_read_b128 v[218:221], v79 offset:56704
	s_waitcnt lgkmcnt(8)
	v_mfma_f32_16x16x32_bf16 v[166:169], v[222:225], v[230:233], v[166:169]
	ds_read_b128 v[222:225], v79 offset:61056
	s_waitcnt lgkmcnt(8)
	v_mfma_f32_16x16x32_bf16 v[52:55], v[198:201], v[230:233], v[52:55]
	ds_read_b128 v[198:201], v79 offset:65408
	s_waitcnt lgkmcnt(7)
	v_mfma_f32_16x16x32_bf16 v[48:51], v[194:197], v[226:229], v[48:51]
	s_waitcnt lgkmcnt(6)
	v_mfma_f32_16x16x32_bf16 v[56:59], v[202:205], v[226:229], v[56:59]
	s_waitcnt lgkmcnt(5)
	v_mfma_f32_16x16x32_bf16 v[60:63], v[206:209], v[226:229], v[60:63]
	s_waitcnt lgkmcnt(4)
	v_mfma_f32_16x16x32_bf16 v[64:67], v[210:213], v[226:229], v[64:67]
	s_waitcnt lgkmcnt(3)
	v_mfma_f32_16x16x32_bf16 v[100:103], v[214:217], v[226:229], v[100:103]
	s_waitcnt lgkmcnt(2)
	v_mfma_f32_16x16x32_bf16 v[104:107], v[218:221], v[226:229], v[104:107]
	s_waitcnt lgkmcnt(1)
	v_mfma_f32_16x16x32_bf16 v[166:169], v[222:225], v[226:229], v[166:169]
	s_waitcnt lgkmcnt(0)
	v_mfma_f32_16x16x32_bf16 v[174:177], v[198:201], v[226:229], v[52:55]
	ds_read_b128 v[178:181], v78 offset:192
	ds_read_b128 v[230:233], v79 offset:35008
	ds_read_b128 v[194:197], v79 offset:39360
	ds_read_b128 v[202:205], v79 offset:43712
	ds_read_b128 v[206:209], v79 offset:48064
	ds_read_b128 v[210:213], v79 offset:52416
	ds_read_b128 v[214:217], v79 offset:56768
	ds_read_b128 v[218:221], v79 offset:61120
	ds_read_b128 v[222:225], v79 offset:65472
	ds_read_b128 v[198:201], v131
	ds_read_b128 v[226:229], v132
	s_nop 1
	v_mov_b32_e32 v3, v130
	s_waitcnt lgkmcnt(9)
	v_mfma_f32_16x16x32_bf16 v[182:185], v[230:233], v[178:181], v[48:51]
	ds_read_b128 v[230:233], v133
	s_nop 2
	s_waitcnt lgkmcnt(9)
	v_mfma_f32_16x16x32_bf16 v[186:189], v[194:197], v[178:181], v[56:59]
	ds_read_b128 v[194:197], v134
	s_waitcnt lgkmcnt(9)
	v_mfma_f32_16x16x32_bf16 v[190:193], v[202:205], v[178:181], v[60:63]
	ds_read_b128 v[202:205], v135
	s_waitcnt lgkmcnt(9)
	v_mfma_f32_16x16x32_bf16 v[64:67], v[206:209], v[178:181], v[64:67]
	ds_read_b128 v[206:209], v136
	s_waitcnt lgkmcnt(9)
	v_mfma_f32_16x16x32_bf16 v[60:63], v[210:213], v[178:181], v[100:103]
	ds_read_b128 v[210:213], v137
	s_waitcnt lgkmcnt(9)
	v_mfma_f32_16x16x32_bf16 v[56:59], v[214:217], v[178:181], v[104:107]
	ds_read_b128 v[214:217], v138
	s_waitcnt lgkmcnt(9)
	v_mfma_f32_16x16x32_bf16 v[52:55], v[218:221], v[178:181], v[166:169]
	ds_read_b128 v[218:221], v139
	s_waitcnt lgkmcnt(9)
	v_mfma_f32_16x16x32_bf16 v[48:51], v[222:225], v[178:181], v[174:177]
	ds_read_b128 v[222:225], v140
	s_waitcnt lgkmcnt(9)
	v_sub_f32_e32 v0, v75, v198
	v_sub_f32_e32 v1, v75, v199
	v_sub_f32_e32 v100, v75, v200
	v_sub_f32_e32 v101, v75, v201
	ds_read_b128 v[198:201], v141
	v_mul_f32_e32 v0, 0x3fb8aa3b, v0
	v_mul_f32_e32 v1, 0x3fb8aa3b, v1
	v_mul_f32_e32 v100, 0x3fb8aa3b, v100
	v_mul_f32_e32 v101, 0x3fb8aa3b, v101
	v_exp_f32_e32 v0, v0
	v_exp_f32_e32 v1, v1
	v_exp_f32_e32 v100, v100
	v_exp_f32_e32 v101, v101
	v_pk_mul_f32 v[0:1], v[182:183], v[0:1]
	s_waitcnt lgkmcnt(9)
	v_pk_mul_f32 v[0:1], v[226:227], v[0:1]
	v_pk_mul_f32 v[100:101], v[184:185], v[100:101]
	s_nop 0
	v_pk_mul_f32 v[100:101], v[228:229], v[100:101]
	ds_read_b128 v[226:229], v142
	s_waitcnt lgkmcnt(9)
	v_sub_f32_e32 v102, v75, v230
	v_sub_f32_e32 v103, v75, v231
	v_sub_f32_e32 v104, v75, v232
	v_sub_f32_e32 v105, v75, v233
	ds_read_b128 v[230:233], v143
	v_mul_f32_e32 v102, 0x3fb8aa3b, v102
	v_mul_f32_e32 v103, 0x3fb8aa3b, v103
	v_mul_f32_e32 v104, 0x3fb8aa3b, v104
	v_mul_f32_e32 v105, 0x3fb8aa3b, v105
	v_exp_f32_e32 v102, v102
	v_exp_f32_e32 v103, v103
	v_exp_f32_e32 v104, v104
	v_exp_f32_e32 v105, v105
	v_pk_mul_f32 v[102:103], v[186:187], v[102:103]
	s_waitcnt lgkmcnt(9)
	v_pk_mul_f32 v[102:103], v[194:195], v[102:103]
	v_pk_mul_f32 v[104:105], v[188:189], v[104:105]
	s_nop 0
	v_pk_mul_f32 v[104:105], v[196:197], v[104:105]
	ds_read_b128 v[194:197], v144
	s_waitcnt lgkmcnt(9)
	v_sub_f32_e32 v106, v75, v202
	v_sub_f32_e32 v107, v75, v203
	v_sub_f32_e32 v108, v75, v204
	v_sub_f32_e32 v109, v75, v205
	ds_read_b128 v[202:205], v148
	v_mul_f32_e32 v106, 0x3fb8aa3b, v106
	v_mul_f32_e32 v107, 0x3fb8aa3b, v107
	v_mul_f32_e32 v108, 0x3fb8aa3b, v108
	v_mul_f32_e32 v109, 0x3fb8aa3b, v109
	v_exp_f32_e32 v106, v106
	v_exp_f32_e32 v107, v107
	v_exp_f32_e32 v108, v108
	v_exp_f32_e32 v109, v109
	v_pk_mul_f32 v[106:107], v[190:191], v[106:107]
	s_waitcnt lgkmcnt(9)
	v_pk_mul_f32 v[106:107], v[206:207], v[106:107]
	v_pk_mul_f32 v[108:109], v[192:193], v[108:109]
	s_nop 0
	v_pk_mul_f32 v[108:109], v[208:209], v[108:109]
	ds_read_b128 v[206:209], v149
	s_waitcnt lgkmcnt(9)
	v_sub_f32_e32 v166, v75, v210
	v_sub_f32_e32 v167, v75, v211
	v_mul_f32_e32 v166, 0x3fb8aa3b, v166
	v_mul_f32_e32 v167, 0x3fb8aa3b, v167
	v_exp_f32_e32 v166, v166
	v_exp_f32_e32 v167, v167
	s_nop 0
	v_pk_mul_f32 v[64:65], v[64:65], v[166:167]
	v_sub_f32_e32 v166, v75, v212
	v_sub_f32_e32 v167, v75, v213
	v_mul_f32_e32 v166, 0x3fb8aa3b, v166
	v_mul_f32_e32 v167, 0x3fb8aa3b, v167
	v_exp_f32_e32 v166, v166
	v_exp_f32_e32 v167, v167
	s_waitcnt lgkmcnt(8)
	v_pk_mul_f32 v[64:65], v[214:215], v[64:65]
	v_pk_mul_f32 v[66:67], v[66:67], v[166:167]
	s_nop 0
	v_pk_mul_f32 v[66:67], v[216:217], v[66:67]
	s_waitcnt lgkmcnt(7)
	v_sub_f32_e32 v166, v75, v218
	v_sub_f32_e32 v167, v75, v219
	v_mul_f32_e32 v166, 0x3fb8aa3b, v166
	v_mul_f32_e32 v167, 0x3fb8aa3b, v167
	v_exp_f32_e32 v166, v166
	v_exp_f32_e32 v167, v167
	s_nop 0
	v_pk_mul_f32 v[60:61], v[60:61], v[166:167]
	v_sub_f32_e32 v166, v75, v220
	v_sub_f32_e32 v167, v75, v221
	v_mul_f32_e32 v166, 0x3fb8aa3b, v166
	v_mul_f32_e32 v167, 0x3fb8aa3b, v167
	v_exp_f32_e32 v166, v166
	v_exp_f32_e32 v167, v167
	s_waitcnt lgkmcnt(6)
	v_pk_mul_f32 v[60:61], v[222:223], v[60:61]
	v_pk_mul_f32 v[62:63], v[62:63], v[166:167]
	s_nop 0
	v_pk_mul_f32 v[62:63], v[224:225], v[62:63]
	s_waitcnt lgkmcnt(5)
	v_sub_f32_e32 v166, v75, v198
	v_sub_f32_e32 v167, v75, v199
	v_mul_f32_e32 v166, 0x3fb8aa3b, v166
	v_mul_f32_e32 v167, 0x3fb8aa3b, v167
	v_exp_f32_e32 v166, v166
	v_exp_f32_e32 v167, v167
	s_nop 0
	v_pk_mul_f32 v[56:57], v[56:57], v[166:167]
	v_sub_f32_e32 v166, v75, v200
	v_sub_f32_e32 v167, v75, v201
	v_mul_f32_e32 v166, 0x3fb8aa3b, v166
	v_mul_f32_e32 v167, 0x3fb8aa3b, v167
	v_exp_f32_e32 v166, v166
	v_exp_f32_e32 v167, v167
	s_waitcnt lgkmcnt(4)
	v_pk_mul_f32 v[56:57], v[226:227], v[56:57]
	v_pk_mul_f32 v[58:59], v[58:59], v[166:167]
	s_nop 0
	v_pk_mul_f32 v[58:59], v[228:229], v[58:59]
	s_waitcnt lgkmcnt(3)
	v_sub_f32_e32 v166, v75, v230
	v_sub_f32_e32 v167, v75, v231
	v_mul_f32_e32 v166, 0x3fb8aa3b, v166
	v_mul_f32_e32 v167, 0x3fb8aa3b, v167
	v_exp_f32_e32 v166, v166
	v_exp_f32_e32 v167, v167
	s_nop 0
	v_pk_mul_f32 v[52:53], v[52:53], v[166:167]
	v_sub_f32_e32 v166, v75, v232
	v_sub_f32_e32 v167, v75, v233
	v_mul_f32_e32 v166, 0x3fb8aa3b, v166
	v_mul_f32_e32 v167, 0x3fb8aa3b, v167
	v_exp_f32_e32 v166, v166
	v_exp_f32_e32 v167, v167
	s_waitcnt lgkmcnt(2)
	v_pk_mul_f32 v[52:53], v[194:195], v[52:53]
	v_pk_mul_f32 v[54:55], v[54:55], v[166:167]
	s_nop 0
	v_pk_mul_f32 v[54:55], v[196:197], v[54:55]
	s_waitcnt lgkmcnt(1)
	v_sub_f32_e32 v166, v75, v202
	v_sub_f32_e32 v167, v75, v203
	v_mul_f32_e32 v166, 0x3fb8aa3b, v166
	v_mul_f32_e32 v167, 0x3fb8aa3b, v167
	v_exp_f32_e32 v166, v166
	v_exp_f32_e32 v167, v167
	s_nop 0
	v_pk_mul_f32 v[48:49], v[48:49], v[166:167]
	v_sub_f32_e32 v166, v75, v204
	v_sub_f32_e32 v167, v75, v205
	v_mul_f32_e32 v166, 0x3fb8aa3b, v166
	v_mul_f32_e32 v167, 0x3fb8aa3b, v167
	v_exp_f32_e32 v166, v166
	v_exp_f32_e32 v167, v167
	s_waitcnt lgkmcnt(0)
	v_pk_mul_f32 v[48:49], v[206:207], v[48:49]
	v_pk_mul_f32 v[50:51], v[50:51], v[166:167]
	s_nop 0
	v_pk_mul_f32 v[50:51], v[208:209], v[50:51]
	v_cvt_pk_bf16_f32 v0, v0, v1
	v_cmp_lt_i32_e32 vcc, -1, v3
	s_nop 1
	v_cndmask_b32_e32 v1, 0, v0, vcc
	v_lshrrev_b32_e32 v0, 16, v0
	v_cmp_lt_i32_e32 vcc, 0, v3
	s_nop 1
	v_cndmask_b32_e32 v0, 0, v0, vcc
	v_perm_b32 v166, v0, v1, s69
	v_cvt_pk_bf16_f32 v0, v100, v101
	v_cmp_lt_i32_e32 vcc, 1, v3
	s_nop 1
	v_cndmask_b32_e32 v1, 0, v0, vcc
	v_lshrrev_b32_e32 v0, 16, v0
	v_cmp_lt_i32_e32 vcc, 2, v3
	s_nop 1
	v_cndmask_b32_e32 v0, 0, v0, vcc
	v_perm_b32 v167, v0, v1, s69
	v_cvt_pk_bf16_f32 v0, v102, v103
	v_cmp_lt_i32_e32 vcc, 15, v3
	s_nop 1
	v_cndmask_b32_e32 v1, 0, v0, vcc
	v_lshrrev_b32_e32 v0, 16, v0
	v_cmp_lt_i32_e32 vcc, 16, v3
	s_nop 1
	v_cndmask_b32_e32 v0, 0, v0, vcc
	v_perm_b32 v168, v0, v1, s69
	v_add_u32_e32 v1, v145, v146
	ds_read_b64_tr_b16 v[102:103], v1 offset:1280
	ds_read_b64_tr_b16 v[100:101], v1
	ds_read_b64_tr_b16 v[176:177], v1 offset:1312
	ds_read_b64_tr_b16 v[174:175], v1 offset:32
	v_cvt_pk_bf16_f32 v0, v104, v105
	v_cmp_lt_i32_e32 vcc, 17, v3
	s_nop 1
	v_cndmask_b32_e32 v104, 0, v0, vcc
	v_lshrrev_b32_e32 v0, 16, v0
	v_cmp_lt_i32_e32 vcc, 18, v3
	s_nop 1
	v_cndmask_b32_e32 v0, 0, v0, vcc
	v_perm_b32 v169, v0, v104, s69
	s_nop 0
	s_waitcnt lgkmcnt(2)
	v_mfma_f32_16x16x32_bf16 v[100:103], v[100:103], v[166:169], 0
	s_waitcnt lgkmcnt(0)
	v_mfma_f32_16x16x32_bf16 v[166:169], v[174:177], v[166:169], 0
	v_cvt_pk_bf16_f32 v0, v106, v107
	v_cmp_lt_i32_e32 vcc, 31, v3
	s_nop 1
	v_cndmask_b32_e32 v104, 0, v0, vcc
	v_lshrrev_b32_e32 v0, 16, v0
	v_cmp_lt_i32_e32 vcc, 32, v3
	s_nop 1
	v_cndmask_b32_e32 v0, 0, v0, vcc
	v_perm_b32 v104, v0, v104, s69
	v_cvt_pk_bf16_f32 v0, v108, v109
	v_cmp_lt_i32_e32 vcc, 33, v3
	s_nop 1
	v_cndmask_b32_e32 v105, 0, v0, vcc
	v_lshrrev_b32_e32 v0, 16, v0
	v_cmp_lt_i32_e32 vcc, 34, v3
	s_nop 1
	v_cndmask_b32_e32 v0, 0, v0, vcc
	v_perm_b32 v105, v0, v105, s69
	v_cvt_pk_bf16_f32 v0, v64, v65
	v_cmp_lt_i32_e32 vcc, 47, v3
	s_nop 1
	v_cndmask_b32_e32 v64, 0, v0, vcc
	v_lshrrev_b32_e32 v0, 16, v0
	v_cmp_lt_i32_e32 vcc, 48, v3
	s_nop 1
	v_cndmask_b32_e32 v0, 0, v0, vcc
	v_perm_b32 v106, v0, v64, s69
	v_cvt_pk_bf16_f32 v0, v66, v67
	v_cmp_lt_i32_e32 vcc, 49, v3
	s_nop 1
	v_cndmask_b32_e32 v64, 0, v0, vcc
	v_lshrrev_b32_e32 v0, 16, v0
	v_cmp_lt_i32_e32 vcc, 50, v3
	s_nop 1
	v_cndmask_b32_e32 v0, 0, v0, vcc
	v_perm_b32 v107, v0, v64, s69
	ds_read_b64_tr_b16 v[66:67], v1 offset:3840
	ds_read_b64_tr_b16 v[64:65], v1 offset:2560
	ds_read_b64_tr_b16 v[174:175], v1 offset:2592
	ds_read_b64_tr_b16 v[176:177], v1 offset:3872
	s_waitcnt lgkmcnt(2)
	v_mfma_f32_16x16x32_bf16 v[64:67], v[64:67], v[104:107], v[100:103]
	s_waitcnt lgkmcnt(0)
	v_mfma_f32_16x16x32_bf16 v[100:103], v[174:177], v[104:107], v[166:169]
	v_cvt_pk_bf16_f32 v0, v60, v61
	v_cmp_lt_i32_e32 vcc, 63, v3
	s_nop 1
	v_cndmask_b32_e32 v60, 0, v0, vcc
	v_lshrrev_b32_e32 v0, 16, v0
	v_cmp_lt_i32_e32 vcc, 64, v3
	s_nop 1
	v_cndmask_b32_e32 v0, 0, v0, vcc
	v_perm_b32 v60, v0, v60, s69
	v_cvt_pk_bf16_f32 v0, v62, v63
	v_cmp_lt_i32_e32 vcc, s86, v3
	s_nop 1
	v_cndmask_b32_e32 v61, 0, v0, vcc
	v_lshrrev_b32_e32 v0, 16, v0
	v_cmp_lt_i32_e32 vcc, s88, v3
	s_nop 1
	v_cndmask_b32_e32 v0, 0, v0, vcc
	v_perm_b32 v61, v0, v61, s69
	v_cvt_pk_bf16_f32 v0, v56, v57
	v_cmp_lt_i32_e32 vcc, s52, v3
	s_nop 1
	v_cndmask_b32_e32 v56, 0, v0, vcc
	v_lshrrev_b32_e32 v0, 16, v0
	v_cmp_lt_i32_e32 vcc, s97, v3
	s_nop 1
	v_cndmask_b32_e32 v0, 0, v0, vcc
	v_perm_b32 v62, v0, v56, s69
	v_cvt_pk_bf16_f32 v0, v58, v59
	v_cmp_lt_i32_e32 vcc, s53, v3
	s_nop 1
	v_cndmask_b32_e32 v56, 0, v0, vcc
	v_lshrrev_b32_e32 v0, 16, v0
	v_cmp_lt_i32_e32 vcc, s54, v3
	s_nop 1
	v_cndmask_b32_e32 v0, 0, v0, vcc
	v_perm_b32 v63, v0, v56, s69
	ds_read_b64_tr_b16 v[58:59], v1 offset:6400
	ds_read_b64_tr_b16 v[56:57], v1 offset:5120
	ds_read_b64_tr_b16 v[104:105], v1 offset:5152
	ds_read_b64_tr_b16 v[106:107], v1 offset:6432
	s_waitcnt lgkmcnt(2)
	v_mfma_f32_16x16x32_bf16 v[56:59], v[56:59], v[60:63], v[64:67]
	s_waitcnt lgkmcnt(0)
	v_mfma_f32_16x16x32_bf16 v[60:63], v[104:107], v[60:63], v[100:103]
	v_cvt_pk_bf16_f32 v0, v52, v53
	v_cmp_lt_i32_e32 vcc, s55, v3
	s_movk_i32 s14, 0x6f
	s_nop 0
	v_cndmask_b32_e32 v52, 0, v0, vcc
	v_lshrrev_b32_e32 v0, 16, v0
	v_cmp_lt_i32_e32 vcc, s68, v3
	s_nop 1
	v_cndmask_b32_e32 v0, 0, v0, vcc
	v_perm_b32 v52, v0, v52, s69
	v_cvt_pk_bf16_f32 v0, v54, v55
	v_cmp_lt_i32_e32 vcc, s56, v3
	s_nop 1
	v_cndmask_b32_e32 v53, 0, v0, vcc
	v_lshrrev_b32_e32 v0, 16, v0
	v_cmp_lt_i32_e32 vcc, s57, v3
	s_nop 1
	v_cndmask_b32_e32 v0, 0, v0, vcc
	v_perm_b32 v53, v0, v53, s69
	v_cvt_pk_bf16_f32 v0, v48, v49
	v_cmp_lt_i32_e32 vcc, s14, v3
	s_movk_i32 s14, 0x70
	s_nop 0
	v_cndmask_b32_e32 v48, 0, v0, vcc
	v_lshrrev_b32_e32 v0, 16, v0
	v_cmp_lt_i32_e32 vcc, s14, v3
	s_movk_i32 s14, 0x71
	s_nop 0
	v_cndmask_b32_e32 v0, 0, v0, vcc
	v_perm_b32 v54, v0, v48, s69
	v_cvt_pk_bf16_f32 v0, v50, v51
	v_cmp_lt_i32_e32 vcc, s14, v3
	s_movk_i32 s14, 0x72
	s_nop 0
	v_cndmask_b32_e32 v48, 0, v0, vcc
	v_lshrrev_b32_e32 v0, 16, v0
	v_cmp_lt_i32_e32 vcc, s14, v3
	s_mov_b64 s[14:15], 0
	s_nop 0
	v_cndmask_b32_e32 v0, 0, v0, vcc
	v_perm_b32 v55, v0, v48, s69
	ds_read_b64_tr_b16 v[50:51], v1 offset:8960
	ds_read_b64_tr_b16 v[48:49], v1 offset:7680
	ds_read_b64_tr_b16 v[64:65], v1 offset:7712
	ds_read_b64_tr_b16 v[66:67], v1 offset:8992
	s_waitcnt lgkmcnt(2)
	v_mfma_f32_16x16x32_bf16 v[48:51], v[48:51], v[52:55], v[56:59]
	s_waitcnt lgkmcnt(0)
	v_mfma_f32_16x16x32_bf16 v[52:55], v[64:67], v[52:55], v[60:63]

.LBB0_1297:
	v_lshl_add_u32 v144, s45, 8, v148
	v_lshl_or_b32 v142, s46, 8, v150
	v_lshlrev_b32_e32 v145, 1, v142
	v_lshl_add_u32 v145, v144, 12, v145
	v_lshlrev_b32_e32 v143, 2, v142
	v_lshl_add_u32 v143, v144, 13, v143
	global_load_dwordx2 v[174:175], v145, s[10:11]
	global_load_dwordx2 v[176:177], v145, s[10:11] offset:32
	global_load_dwordx2 v[178:179], v145, s[10:11] offset:256
	global_load_dwordx2 v[180:181], v145, s[10:11] offset:288
	v_add_u32_e32 v132, 0x10000, v145
	global_load_dwordx2 v[182:183], v132, s[10:11]
	global_load_dwordx2 v[184:185], v132, s[10:11] offset:32
	global_load_dwordx2 v[186:187], v132, s[10:11] offset:256
	global_load_dwordx2 v[188:189], v132, s[10:11] offset:288
	v_add_u32_e32 v132, 0x20000, v145
	global_load_dwordx2 v[190:191], v132, s[10:11]
	global_load_dwordx2 v[192:193], v132, s[10:11] offset:32
	global_load_dwordx2 v[194:195], v132, s[10:11] offset:256
	global_load_dwordx2 v[196:197], v132, s[10:11] offset:288
	v_add_u32_e32 v132, 0x30000, v145
	global_load_dwordx2 v[198:199], v132, s[10:11]
	global_load_dwordx2 v[200:201], v132, s[10:11] offset:32
	global_load_dwordx2 v[202:203], v132, s[10:11] offset:256
	global_load_dwordx2 v[204:205], v132, s[10:11] offset:288
	v_add_u32_e32 v132, 0x80000, v145
	global_load_dwordx2 v[206:207], v132, s[10:11]
	global_load_dwordx2 v[208:209], v132, s[10:11] offset:32
	global_load_dwordx2 v[210:211], v132, s[10:11] offset:256
	global_load_dwordx2 v[212:213], v132, s[10:11] offset:288
	v_add_u32_e32 v132, 0x90000, v145
	global_load_dwordx2 v[214:215], v132, s[10:11]
	global_load_dwordx2 v[216:217], v132, s[10:11] offset:32
	global_load_dwordx2 v[218:219], v132, s[10:11] offset:256
	global_load_dwordx2 v[220:221], v132, s[10:11] offset:288
	v_add_u32_e32 v132, 0xa0000, v145
	global_load_dwordx2 v[222:223], v132, s[10:11]
	global_load_dwordx2 v[224:225], v132, s[10:11] offset:32
	global_load_dwordx2 v[226:227], v132, s[10:11] offset:256
	global_load_dwordx2 v[228:229], v132, s[10:11] offset:288
	v_add_u32_e32 v132, 0xb0000, v145
	global_load_dwordx2 v[230:231], v132, s[10:11]
	global_load_dwordx2 v[232:233], v132, s[10:11] offset:32
	global_load_dwordx2 v[234:235], v132, s[10:11] offset:256
	global_load_dwordx2 v[146:147], v132, s[10:11] offset:288
	s_waitcnt vmcnt(31)
	v_lshlrev_b32_e32 v154, 16, v174
	v_and_b32_e32 v155, 0xffff0000, v174
	v_lshlrev_b32_e32 v156, 16, v175
	v_and_b32_e32 v157, 0xffff0000, v175
	v_pk_add_f32 v[126:127], v[126:127], v[156:157]
	v_pk_add_f32 v[124:125], v[124:125], v[154:155]
	global_store_dwordx4 v143, v[124:127], s[58:59]
	s_waitcnt vmcnt(31)
	v_lshlrev_b32_e32 v154, 16, v176
	v_and_b32_e32 v155, 0xffff0000, v176
	v_lshlrev_b32_e32 v156, 16, v177
	v_and_b32_e32 v157, 0xffff0000, v177
	v_pk_add_f32 v[122:123], v[122:123], v[156:157]
	v_pk_add_f32 v[120:121], v[120:121], v[154:155]
	global_store_dwordx4 v143, v[120:123], s[58:59] offset:64
	s_waitcnt vmcnt(31)
	v_lshlrev_b32_e32 v154, 16, v178
	v_and_b32_e32 v155, 0xffff0000, v178
	v_lshlrev_b32_e32 v156, 16, v179
	v_and_b32_e32 v157, 0xffff0000, v179
	v_pk_add_f32 v[118:119], v[118:119], v[156:157]
	v_pk_add_f32 v[116:117], v[116:117], v[154:155]
	global_store_dwordx4 v143, v[116:119], s[58:59] offset:512
	s_waitcnt vmcnt(31)
	v_lshlrev_b32_e32 v154, 16, v180
	v_and_b32_e32 v155, 0xffff0000, v180
	v_lshlrev_b32_e32 v156, 16, v181
	v_and_b32_e32 v157, 0xffff0000, v181
	v_pk_add_f32 v[114:115], v[114:115], v[156:157]
	v_pk_add_f32 v[112:113], v[112:113], v[154:155]
	global_store_dwordx4 v143, v[112:115], s[58:59] offset:576
	v_add_u32_e32 v132, 0x20000, v143
	s_waitcnt vmcnt(31)
	v_lshlrev_b32_e32 v154, 16, v182
	v_and_b32_e32 v155, 0xffff0000, v182
	v_lshlrev_b32_e32 v156, 16, v183
	v_and_b32_e32 v157, 0xffff0000, v183
	v_pk_add_f32 v[110:111], v[110:111], v[156:157]
	v_pk_add_f32 v[108:109], v[108:109], v[154:155]
	global_store_dwordx4 v132, v[108:111], s[58:59]
	s_waitcnt vmcnt(31)
	v_lshlrev_b32_e32 v154, 16, v184
	v_and_b32_e32 v155, 0xffff0000, v184
	v_lshlrev_b32_e32 v156, 16, v185
	v_and_b32_e32 v157, 0xffff0000, v185
	v_pk_add_f32 v[106:107], v[106:107], v[156:157]
	v_pk_add_f32 v[104:105], v[104:105], v[154:155]
	global_store_dwordx4 v132, v[104:107], s[58:59] offset:64
	s_waitcnt vmcnt(31)
	v_lshlrev_b32_e32 v154, 16, v186
	v_and_b32_e32 v155, 0xffff0000, v186
	v_lshlrev_b32_e32 v156, 16, v187
	v_and_b32_e32 v157, 0xffff0000, v187
	v_pk_add_f32 v[102:103], v[102:103], v[156:157]
	v_pk_add_f32 v[100:101], v[100:101], v[154:155]
	global_store_dwordx4 v132, v[100:103], s[58:59] offset:512
	s_waitcnt vmcnt(31)
	v_lshlrev_b32_e32 v154, 16, v188
	v_and_b32_e32 v155, 0xffff0000, v188
	v_lshlrev_b32_e32 v156, 16, v189
	v_and_b32_e32 v157, 0xffff0000, v189
	v_pk_add_f32 v[98:99], v[98:99], v[156:157]
	v_pk_add_f32 v[96:97], v[96:97], v[154:155]
	global_store_dwordx4 v132, v[96:99], s[58:59] offset:576
	v_add_u32_e32 v132, 0x40000, v143
	s_waitcnt vmcnt(31)
	v_lshlrev_b32_e32 v154, 16, v190
	v_and_b32_e32 v155, 0xffff0000, v190
	v_lshlrev_b32_e32 v156, 16, v191
	v_and_b32_e32 v157, 0xffff0000, v191
	v_pk_add_f32 v[94:95], v[94:95], v[156:157]
	v_pk_add_f32 v[92:93], v[92:93], v[154:155]
	global_store_dwordx4 v132, v[92:95], s[58:59]
	s_waitcnt vmcnt(31)
	v_lshlrev_b32_e32 v154, 16, v192
	v_and_b32_e32 v155, 0xffff0000, v192
	v_lshlrev_b32_e32 v156, 16, v193
	v_and_b32_e32 v157, 0xffff0000, v193
	v_pk_add_f32 v[90:91], v[90:91], v[156:157]
	v_pk_add_f32 v[88:89], v[88:89], v[154:155]
	global_store_dwordx4 v132, v[88:91], s[58:59] offset:64
	s_waitcnt vmcnt(31)
	v_lshlrev_b32_e32 v154, 16, v194
	v_and_b32_e32 v155, 0xffff0000, v194
	v_lshlrev_b32_e32 v156, 16, v195
	v_and_b32_e32 v157, 0xffff0000, v195
	v_pk_add_f32 v[86:87], v[86:87], v[156:157]
	v_pk_add_f32 v[84:85], v[84:85], v[154:155]
	global_store_dwordx4 v132, v[84:87], s[58:59] offset:512
	s_waitcnt vmcnt(31)
	v_lshlrev_b32_e32 v154, 16, v196
	v_and_b32_e32 v155, 0xffff0000, v196
	v_lshlrev_b32_e32 v156, 16, v197
	v_and_b32_e32 v157, 0xffff0000, v197
	v_pk_add_f32 v[82:83], v[82:83], v[156:157]
	v_pk_add_f32 v[80:81], v[80:81], v[154:155]
	global_store_dwordx4 v132, v[80:83], s[58:59] offset:576
	v_add_u32_e32 v132, 0x60000, v143
	s_waitcnt vmcnt(31)
	v_lshlrev_b32_e32 v154, 16, v198
	v_and_b32_e32 v155, 0xffff0000, v198
	v_lshlrev_b32_e32 v156, 16, v199
	v_and_b32_e32 v157, 0xffff0000, v199
	v_pk_add_f32 v[78:79], v[78:79], v[156:157]
	v_pk_add_f32 v[76:77], v[76:77], v[154:155]
	global_store_dwordx4 v132, v[76:79], s[58:59]
	s_waitcnt vmcnt(31)
	v_lshlrev_b32_e32 v154, 16, v200
	v_and_b32_e32 v155, 0xffff0000, v200
	v_lshlrev_b32_e32 v156, 16, v201
	v_and_b32_e32 v157, 0xffff0000, v201
	v_pk_add_f32 v[74:75], v[74:75], v[156:157]
	v_pk_add_f32 v[72:73], v[72:73], v[154:155]
	global_store_dwordx4 v132, v[72:75], s[58:59] offset:64
	s_waitcnt vmcnt(31)
	v_lshlrev_b32_e32 v154, 16, v202
	v_and_b32_e32 v155, 0xffff0000, v202
	v_lshlrev_b32_e32 v156, 16, v203
	v_and_b32_e32 v157, 0xffff0000, v203
	v_pk_add_f32 v[70:71], v[70:71], v[156:157]
	v_pk_add_f32 v[68:69], v[68:69], v[154:155]
	global_store_dwordx4 v132, v[68:71], s[58:59] offset:512
	s_waitcnt vmcnt(31)
	v_lshlrev_b32_e32 v154, 16, v204
	v_and_b32_e32 v155, 0xffff0000, v204
	v_lshlrev_b32_e32 v156, 16, v205
	v_and_b32_e32 v157, 0xffff0000, v205
	v_pk_add_f32 v[66:67], v[66:67], v[156:157]
	v_pk_add_f32 v[64:65], v[64:65], v[154:155]
	global_store_dwordx4 v132, v[64:67], s[58:59] offset:576
	v_add_u32_e32 v132, 0x100000, v143
	s_waitcnt vmcnt(31)
	v_lshlrev_b32_e32 v154, 16, v206
	v_and_b32_e32 v155, 0xffff0000, v206
	v_lshlrev_b32_e32 v156, 16, v207
	v_and_b32_e32 v157, 0xffff0000, v207
	v_pk_add_f32 v[62:63], v[62:63], v[156:157]
	v_pk_add_f32 v[60:61], v[60:61], v[154:155]
	global_store_dwordx4 v132, v[60:63], s[58:59]
	s_waitcnt vmcnt(31)
	v_lshlrev_b32_e32 v154, 16, v208
	v_and_b32_e32 v155, 0xffff0000, v208
	v_lshlrev_b32_e32 v156, 16, v209
	v_and_b32_e32 v157, 0xffff0000, v209
	v_pk_add_f32 v[58:59], v[58:59], v[156:157]
	v_pk_add_f32 v[56:57], v[56:57], v[154:155]
	global_store_dwordx4 v132, v[56:59], s[58:59] offset:64
	s_waitcnt vmcnt(31)
	v_lshlrev_b32_e32 v154, 16, v210
	v_and_b32_e32 v155, 0xffff0000, v210
	v_lshlrev_b32_e32 v156, 16, v211
	v_and_b32_e32 v157, 0xffff0000, v211
	v_pk_add_f32 v[54:55], v[54:55], v[156:157]
	v_pk_add_f32 v[52:53], v[52:53], v[154:155]
	global_store_dwordx4 v132, v[52:55], s[58:59] offset:512
	s_waitcnt vmcnt(31)
	v_lshlrev_b32_e32 v154, 16, v212
	v_and_b32_e32 v155, 0xffff0000, v212
	v_lshlrev_b32_e32 v156, 16, v213
	v_and_b32_e32 v157, 0xffff0000, v213
	v_pk_add_f32 v[50:51], v[50:51], v[156:157]
	v_pk_add_f32 v[48:49], v[48:49], v[154:155]
	global_store_dwordx4 v132, v[48:51], s[58:59] offset:576
	v_add_u32_e32 v132, 0x120000, v143
	s_waitcnt vmcnt(31)
	v_lshlrev_b32_e32 v154, 16, v214
	v_and_b32_e32 v155, 0xffff0000, v214
	v_lshlrev_b32_e32 v156, 16, v215
	v_and_b32_e32 v157, 0xffff0000, v215
	v_pk_add_f32 v[46:47], v[46:47], v[156:157]
	v_pk_add_f32 v[44:45], v[44:45], v[154:155]
	global_store_dwordx4 v132, v[44:47], s[58:59]
	s_waitcnt vmcnt(31)
	v_lshlrev_b32_e32 v154, 16, v216
	v_and_b32_e32 v155, 0xffff0000, v216
	v_lshlrev_b32_e32 v156, 16, v217
	v_and_b32_e32 v157, 0xffff0000, v217
	v_pk_add_f32 v[42:43], v[42:43], v[156:157]
	v_pk_add_f32 v[40:41], v[40:41], v[154:155]
	global_store_dwordx4 v132, v[40:43], s[58:59] offset:64
	s_waitcnt vmcnt(31)
	v_lshlrev_b32_e32 v154, 16, v218
	v_and_b32_e32 v155, 0xffff0000, v218
	v_lshlrev_b32_e32 v156, 16, v219
	v_and_b32_e32 v157, 0xffff0000, v219
	v_pk_add_f32 v[38:39], v[38:39], v[156:157]
	v_pk_add_f32 v[36:37], v[36:37], v[154:155]
	global_store_dwordx4 v132, v[36:39], s[58:59] offset:512
	s_waitcnt vmcnt(31)
	v_lshlrev_b32_e32 v154, 16, v220
	v_and_b32_e32 v155, 0xffff0000, v220
	v_lshlrev_b32_e32 v156, 16, v221
	v_and_b32_e32 v157, 0xffff0000, v221
	v_pk_add_f32 v[34:35], v[34:35], v[156:157]
	v_pk_add_f32 v[32:33], v[32:33], v[154:155]
	global_store_dwordx4 v132, v[32:35], s[58:59] offset:576
	v_add_u32_e32 v132, 0x140000, v143
	s_waitcnt vmcnt(31)
	v_lshlrev_b32_e32 v154, 16, v222
	v_and_b32_e32 v155, 0xffff0000, v222
	v_lshlrev_b32_e32 v156, 16, v223
	v_and_b32_e32 v157, 0xffff0000, v223
	v_pk_add_f32 v[30:31], v[30:31], v[156:157]
	v_pk_add_f32 v[28:29], v[28:29], v[154:155]
	global_store_dwordx4 v132, v[28:31], s[58:59]
	s_waitcnt vmcnt(31)
	v_lshlrev_b32_e32 v154, 16, v224
	v_and_b32_e32 v155, 0xffff0000, v224
	v_lshlrev_b32_e32 v156, 16, v225
	v_and_b32_e32 v157, 0xffff0000, v225
	v_pk_add_f32 v[26:27], v[26:27], v[156:157]
	v_pk_add_f32 v[24:25], v[24:25], v[154:155]
	global_store_dwordx4 v132, v[24:27], s[58:59] offset:64
	s_waitcnt vmcnt(31)
	v_lshlrev_b32_e32 v154, 16, v226
	v_and_b32_e32 v155, 0xffff0000, v226
	v_lshlrev_b32_e32 v156, 16, v227
	v_and_b32_e32 v157, 0xffff0000, v227
	v_pk_add_f32 v[22:23], v[22:23], v[156:157]
	v_pk_add_f32 v[20:21], v[20:21], v[154:155]
	global_store_dwordx4 v132, v[20:23], s[58:59] offset:512
	s_waitcnt vmcnt(31)
	v_lshlrev_b32_e32 v154, 16, v228
	v_and_b32_e32 v155, 0xffff0000, v228
	v_lshlrev_b32_e32 v156, 16, v229
	v_and_b32_e32 v157, 0xffff0000, v229
	v_pk_add_f32 v[18:19], v[18:19], v[156:157]
	v_pk_add_f32 v[16:17], v[16:17], v[154:155]
	global_store_dwordx4 v132, v[16:19], s[58:59] offset:576
	v_add_u32_e32 v132, 0x160000, v143
	s_waitcnt vmcnt(31)
	v_lshlrev_b32_e32 v154, 16, v230
	v_and_b32_e32 v155, 0xffff0000, v230
	v_lshlrev_b32_e32 v156, 16, v231
	v_and_b32_e32 v157, 0xffff0000, v231
	v_pk_add_f32 v[14:15], v[14:15], v[156:157]
	v_pk_add_f32 v[12:13], v[12:13], v[154:155]
	global_store_dwordx4 v132, v[12:15], s[58:59]
	s_waitcnt vmcnt(31)
	v_lshlrev_b32_e32 v154, 16, v232
	v_and_b32_e32 v155, 0xffff0000, v232
	v_lshlrev_b32_e32 v156, 16, v233
	v_and_b32_e32 v157, 0xffff0000, v233
	v_pk_add_f32 v[10:11], v[10:11], v[156:157]
	v_pk_add_f32 v[8:9], v[8:9], v[154:155]
	global_store_dwordx4 v132, v[8:11], s[58:59] offset:64
	s_waitcnt vmcnt(31)
	v_lshlrev_b32_e32 v154, 16, v234
	v_and_b32_e32 v155, 0xffff0000, v234
	v_lshlrev_b32_e32 v156, 16, v235
	v_and_b32_e32 v157, 0xffff0000, v235
	v_pk_add_f32 v[6:7], v[6:7], v[156:157]
	v_pk_add_f32 v[4:5], v[4:5], v[154:155]
	global_store_dwordx4 v132, v[4:7], s[58:59] offset:512
	s_waitcnt vmcnt(31)
	v_lshlrev_b32_e32 v154, 16, v146
	v_and_b32_e32 v155, 0xffff0000, v146
	v_lshlrev_b32_e32 v156, 16, v147
	v_and_b32_e32 v157, 0xffff0000, v147
	v_pk_add_f32 v[2:3], v[2:3], v[156:157]
	v_pk_add_f32 v[0:1], v[0:1], v[154:155]
	global_store_dwordx4 v132, v[0:3], s[58:59] offset:576
	s_nop 1
.LBB0_1361:
	s_or_b64 exec, exec, s[22:23]
	s_and_b64 vcc, exec, s[0:1]
	s_mov_b64 s[0:1], -1
	s_cbranch_vccnz .LBB0_1282
	s_andn2_b64 vcc, exec, s[8:9]
	s_cbranch_vccnz .LBB0_1281
	s_barrier
	s_branch .LBB0_1281
.LBB0_1372:
	s_waitcnt vmcnt(0)
	s_barrier
	v_and_b32_e32 v23, 63, v172
	v_and_b32_e32 v21, 15, v172
	v_bfe_u32 v22, v172, 4, 2
	v_readfirstlane_b32 s20, v172
	s_add_u32 s0, s92, 0x14500000
	s_addc_u32 s1, s93, 0
	s_add_u32 s2, s92, 0x5c00000
	s_addc_u32 s3, s93, 0
	s_lshr_b32 s17, s20, 6
	s_mov_b32 s16, s76
	s_add_u32 s10, s92, 0x9200000
	s_addc_u32 s11, s93, 0
	v_readlane_b32 s12, v237, 6
	v_readlane_b32 s13, v237, 7
	s_add_u32 s12, s12, 0x4000000
	s_addc_u32 s13, s13, 0
